# back-edge rotation: scalar bookkeeping after the closing barrier moved in front of it in the attention main loop and the P2/P5/P9 GEMM K-loops
# baseline (speedup 1.0000x reference)
.LBB0_212:
	s_ashr_i32 s11, s10, 31
	s_lshl_b64 s[12:13], s[10:11], 19
	s_add_u32 s12, s24, s12
	s_addc_u32 s13, s25, s13
	s_and_b64 s[14:15], s[38:39], exec
	s_cselect_b32 s11, s13, s19
	s_cselect_b32 s42, s12, s18
	s_ashr_i32 s9, s8, 31
	s_lshl_b64 s[14:15], s[8:9], 19
	s_add_u32 s14, s26, s14
	s_addc_u32 s15, s27, s15
	s_and_b64 s[22:23], s[38:39], exec
	s_cselect_b32 s9, s15, s21
	s_cselect_b32 s43, s14, s20
	s_add_u32 s18, s18, 0x40080
	s_addc_u32 s19, s19, 0
	s_add_u32 s44, s20, 0x100
	v_mov_b32_e32 v2, 0
	s_addc_u32 s45, s21, 0
	s_mov_b32 s46, -2
	v_mov_b32_e32 v3, v2
	v_mov_b32_e32 v4, v2
	v_mov_b32_e32 v5, v2
	v_mov_b32_e32 v6, v2
	v_mov_b32_e32 v7, v2
	v_mov_b32_e32 v8, v2
	v_mov_b32_e32 v9, v2
	v_mov_b32_e32 v10, v2
	v_mov_b32_e32 v11, v2
	v_mov_b32_e32 v12, v2
	v_mov_b32_e32 v13, v2
	v_mov_b32_e32 v14, v2
	v_mov_b32_e32 v15, v2
	v_mov_b32_e32 v16, v2
	v_mov_b32_e32 v17, v2
	v_mov_b32_e32 v26, v2
	v_mov_b32_e32 v27, v2
	v_mov_b32_e32 v28, v2
	v_mov_b32_e32 v29, v2
	v_mov_b32_e32 v30, v2
	v_mov_b32_e32 v31, v2
	v_mov_b32_e32 v32, v2
	v_mov_b32_e32 v33, v2
	v_mov_b32_e32 v42, v2
	v_mov_b32_e32 v43, v2
	v_mov_b32_e32 v44, v2
	v_mov_b32_e32 v45, v2
	v_mov_b32_e32 v46, v2
	v_mov_b32_e32 v47, v2
	v_mov_b32_e32 v48, v2
	v_mov_b32_e32 v49, v2
	v_mov_b32_e32 v18, v2
	v_mov_b32_e32 v19, v2
	v_mov_b32_e32 v20, v2
	v_mov_b32_e32 v21, v2
	v_mov_b32_e32 v22, v2
	v_mov_b32_e32 v23, v2
	v_mov_b32_e32 v24, v2
	v_mov_b32_e32 v25, v2
	v_mov_b32_e32 v34, v2
	v_mov_b32_e32 v35, v2
	v_mov_b32_e32 v36, v2
	v_mov_b32_e32 v37, v2
	v_mov_b32_e32 v38, v2
	v_mov_b32_e32 v39, v2
	v_mov_b32_e32 v40, v2
	v_mov_b32_e32 v41, v2
	v_mov_b32_e32 v50, v2
	v_mov_b32_e32 v51, v2
	v_mov_b32_e32 v52, v2
	v_mov_b32_e32 v53, v2
	v_mov_b32_e32 v54, v2
	v_mov_b32_e32 v55, v2
	v_mov_b32_e32 v56, v2
	v_mov_b32_e32 v57, v2
	v_mov_b32_e32 v58, v2
	v_mov_b32_e32 v59, v2
	v_mov_b32_e32 v60, v2
	v_mov_b32_e32 v61, v2
	v_mov_b32_e32 v62, v2
	v_mov_b32_e32 v63, v2
	v_mov_b32_e32 v64, v2
	v_mov_b32_e32 v65, v2
	v_mov_b32_e32 v66, v2
	v_mov_b32_e32 v67, v2
	v_mov_b32_e32 v68, v2
	v_mov_b32_e32 v69, v2
	v_mov_b32_e32 v70, v2
	v_mov_b32_e32 v71, v2
	v_mov_b32_e32 v72, v2
	v_mov_b32_e32 v73, v2
	v_mov_b32_e32 v74, v2
	v_mov_b32_e32 v75, v2
	v_mov_b32_e32 v76, v2
	v_mov_b32_e32 v77, v2
	v_mov_b32_e32 v78, v2
	v_mov_b32_e32 v79, v2
	v_mov_b32_e32 v80, v2
	v_mov_b32_e32 v81, v2
	v_mov_b32_e32 v90, v2
	v_mov_b32_e32 v91, v2
	v_mov_b32_e32 v92, v2
	v_mov_b32_e32 v93, v2
	v_mov_b32_e32 v94, v2
	v_mov_b32_e32 v95, v2
	v_mov_b32_e32 v96, v2
	v_mov_b32_e32 v97, v2
	v_mov_b32_e32 v106, v2
	v_mov_b32_e32 v107, v2
	v_mov_b32_e32 v108, v2
	v_mov_b32_e32 v109, v2
	v_mov_b32_e32 v110, v2
	v_mov_b32_e32 v111, v2
	v_mov_b32_e32 v112, v2
	v_mov_b32_e32 v113, v2
	v_mov_b32_e32 v82, v2
	v_mov_b32_e32 v83, v2
	v_mov_b32_e32 v84, v2
	v_mov_b32_e32 v85, v2
	v_mov_b32_e32 v86, v2
	v_mov_b32_e32 v87, v2
	v_mov_b32_e32 v88, v2
	v_mov_b32_e32 v89, v2
	v_mov_b32_e32 v98, v2
	v_mov_b32_e32 v99, v2
	v_mov_b32_e32 v100, v2
	v_mov_b32_e32 v101, v2
	v_mov_b32_e32 v102, v2
	v_mov_b32_e32 v103, v2
	v_mov_b32_e32 v104, v2
	v_mov_b32_e32 v105, v2
	v_mov_b32_e32 v114, v2
	v_mov_b32_e32 v115, v2
	v_mov_b32_e32 v116, v2
	v_mov_b32_e32 v117, v2
	v_mov_b32_e32 v118, v2
	v_mov_b32_e32 v119, v2
	v_mov_b32_e32 v120, v2
	v_mov_b32_e32 v121, v2
	v_mov_b32_e32 v122, v2
	v_mov_b32_e32 v123, v2
	v_mov_b32_e32 v124, v2
	v_mov_b32_e32 v125, v2
	v_mov_b32_e32 v126, v2
	v_mov_b32_e32 v127, v2
	v_mov_b32_e32 v128, v2
	v_mov_b32_e32 v129, v2
	s_add_u32 s20, s18, 0xfffc0080
	s_addc_u32 s21, s19, -1
	s_add_i32 s48, 0, 0x10000
	s_cmp_eq_u32 s46, 12
	s_cselect_b32 s23, s11, s21
	s_cselect_b32 s22, s42, s20
	s_cselect_b32 s21, s9, s45
	s_cselect_b32 s20, s43, s44
	s_add_i32 s50, 0, 0x14000
.LBB0_213:
	v_add_u32_e32 v156, s48, v141
	v_add_u32_e32 v172, s50, v141
	ds_read_b128 v[144:147], v156
	ds_read_b128 v[148:151], v156 offset:1024
	ds_read_b128 v[152:155], v156 offset:2048
	ds_read_b128 v[156:159], v156 offset:3072
	ds_read_b128 v[160:163], v172
	ds_read_b128 v[164:167], v172 offset:1024
	ds_read_b128 v[168:171], v172 offset:2048
	ds_read_b128 v[172:175], v172 offset:3072
	v_lshl_add_u64 v[180:181], s[18:19], 0, v[136:137]
	s_add_i32 m0, s29, 0xc000
	ds_read_b128 v[176:179], v143
	ds_read_b128 v[186:189], v143 offset:1024
	ds_read_b128 v[190:193], v143 offset:2048
	ds_read_b128 v[212:215], v143 offset:3072
	ds_read_b128 v[216:219], v143 offset:4096
	ds_read_b128 v[220:223], v143 offset:5120
	ds_read_b128 v[224:227], v143 offset:6144
	ds_read_b128 v[228:231], v143 offset:7168
	global_load_lds_dwordx4 v[180:181], off
	v_lshl_add_u64 v[180:181], s[18:19], 0, v[138:139]
	s_add_i32 m0, s29, 0xe000
	s_nop 0
	global_load_lds_dwordx4 v[180:181], off
	s_waitcnt vmcnt(8)
	s_waitcnt lgkmcnt(0)
	s_barrier
	s_setprio 1
	s_waitcnt lgkmcnt(0)
	v_mfma_f32_16x16x32_bf16 v[126:129], v[144:147], v[176:179], v[126:129]
	v_mfma_f32_16x16x32_bf16 v[122:125], v[152:155], v[176:179], v[122:125]
	v_mfma_f32_16x16x32_bf16 v[118:121], v[144:147], v[190:193], v[118:121]
	v_mfma_f32_16x16x32_bf16 v[114:117], v[152:155], v[190:193], v[114:117]
	v_mfma_f32_16x16x32_bf16 v[102:105], v[144:147], v[216:219], v[102:105]
	v_mfma_f32_16x16x32_bf16 v[98:101], v[152:155], v[216:219], v[98:101]
	v_mfma_f32_16x16x32_bf16 v[86:89], v[144:147], v[224:227], v[86:89]
	v_mfma_f32_16x16x32_bf16 v[82:85], v[152:155], v[224:227], v[82:85]
	v_mfma_f32_16x16x32_bf16 v[126:129], v[148:151], v[186:189], v[126:129]
	v_mfma_f32_16x16x32_bf16 v[122:125], v[156:159], v[186:189], v[122:125]
	v_mfma_f32_16x16x32_bf16 v[118:121], v[148:151], v[212:215], v[118:121]
	v_mfma_f32_16x16x32_bf16 v[114:117], v[156:159], v[212:215], v[114:117]
	v_mfma_f32_16x16x32_bf16 v[102:105], v[148:151], v[220:223], v[102:105]
	v_mfma_f32_16x16x32_bf16 v[98:101], v[156:159], v[220:223], v[98:101]
	v_mfma_f32_16x16x32_bf16 v[86:89], v[148:151], v[228:231], v[86:89]
	v_mfma_f32_16x16x32_bf16 v[82:85], v[156:159], v[228:231], v[82:85]
	s_setprio 0
	s_setprio 1
	v_mfma_f32_16x16x32_bf16 v[110:113], v[160:163], v[176:179], v[110:113]
	v_mfma_f32_16x16x32_bf16 v[106:109], v[168:171], v[176:179], v[106:109]
	v_mfma_f32_16x16x32_bf16 v[94:97], v[160:163], v[190:193], v[94:97]
	v_mfma_f32_16x16x32_bf16 v[90:93], v[168:171], v[190:193], v[90:93]
	v_mfma_f32_16x16x32_bf16 v[78:81], v[160:163], v[216:219], v[78:81]
	v_mfma_f32_16x16x32_bf16 v[74:77], v[168:171], v[216:219], v[74:77]
	v_mfma_f32_16x16x32_bf16 v[70:73], v[160:163], v[224:227], v[70:73]
	v_mfma_f32_16x16x32_bf16 v[66:69], v[168:171], v[224:227], v[66:69]
	v_mfma_f32_16x16x32_bf16 v[110:113], v[164:167], v[186:189], v[110:113]
	v_mfma_f32_16x16x32_bf16 v[106:109], v[172:175], v[186:189], v[106:109]
	v_mfma_f32_16x16x32_bf16 v[94:97], v[164:167], v[212:215], v[94:97]
	v_mfma_f32_16x16x32_bf16 v[90:93], v[172:175], v[212:215], v[90:93]
	v_mfma_f32_16x16x32_bf16 v[78:81], v[164:167], v[220:223], v[78:81]
	v_mfma_f32_16x16x32_bf16 v[74:77], v[172:175], v[220:223], v[74:77]
	v_mfma_f32_16x16x32_bf16 v[70:73], v[164:167], v[228:231], v[70:73]
	v_mfma_f32_16x16x32_bf16 v[66:69], v[172:175], v[228:231], v[66:69]
	s_setprio 0
	s_barrier
	s_add_i32 s48, s48, s28
	v_lshl_add_u64 v[180:181], s[20:21], 0, v[0:1]
	s_mov_b32 m0, s48
	ds_read_b128 v[176:179], v143 offset:16384
	ds_read_b128 v[186:189], v143 offset:17408
	ds_read_b128 v[190:193], v143 offset:18432
	ds_read_b128 v[212:215], v143 offset:19456
	ds_read_b128 v[216:219], v143 offset:20480
	ds_read_b128 v[220:223], v143 offset:21504
	ds_read_b128 v[224:227], v143 offset:22528
	ds_read_b128 v[228:231], v143 offset:23552
	global_load_lds_dwordx4 v[180:181], off
	s_add_i32 m0, s48, 0x2000
	s_add_u32 s48, s20, 0x40000
	v_lshl_add_u64 v[194:195], s[20:21], 0, v[130:131]
	s_addc_u32 s49, s21, 0
	s_add_i32 s50, s50, s28
	global_load_lds_dwordx4 v[194:195], off
	v_lshl_add_u64 v[232:233], s[48:49], 0, v[0:1]
	s_mov_b32 m0, s50
	v_lshl_add_u64 v[234:235], s[22:23], 0, v[132:133]
	global_load_lds_dwordx4 v[232:233], off
	v_lshl_add_u64 v[232:233], s[48:49], 0, v[130:131]
	s_add_i32 m0, s50, 0x2000
	s_nop 0
	global_load_lds_dwordx4 v[232:233], off
	v_lshl_add_u64 v[232:233], s[22:23], 0, v[134:135]
	s_mov_b32 m0, s29
	s_nop 0
	global_load_lds_dwordx4 v[232:233], off
	s_mov_b32 m0, s30
	s_nop 0
	global_load_lds_dwordx4 v[234:235], off
	s_waitcnt vmcnt(8)
	s_waitcnt lgkmcnt(0)
	s_barrier
	s_setprio 1
	s_waitcnt lgkmcnt(0)
	v_mfma_f32_16x16x32_bf16 v[62:65], v[144:147], v[176:179], v[62:65]
	v_mfma_f32_16x16x32_bf16 v[58:61], v[152:155], v[176:179], v[58:61]
	v_mfma_f32_16x16x32_bf16 v[54:57], v[144:147], v[190:193], v[54:57]
	v_mfma_f32_16x16x32_bf16 v[50:53], v[152:155], v[190:193], v[50:53]
	v_mfma_f32_16x16x32_bf16 v[38:41], v[144:147], v[216:219], v[38:41]
	v_mfma_f32_16x16x32_bf16 v[34:37], v[152:155], v[216:219], v[34:37]
	v_mfma_f32_16x16x32_bf16 v[22:25], v[144:147], v[224:227], v[22:25]
	v_mfma_f32_16x16x32_bf16 v[18:21], v[152:155], v[224:227], v[18:21]
	v_mfma_f32_16x16x32_bf16 v[62:65], v[148:151], v[186:189], v[62:65]
	v_mfma_f32_16x16x32_bf16 v[58:61], v[156:159], v[186:189], v[58:61]
	v_mfma_f32_16x16x32_bf16 v[54:57], v[148:151], v[212:215], v[54:57]
	v_mfma_f32_16x16x32_bf16 v[50:53], v[156:159], v[212:215], v[50:53]
	v_mfma_f32_16x16x32_bf16 v[38:41], v[148:151], v[220:223], v[38:41]
	v_mfma_f32_16x16x32_bf16 v[34:37], v[156:159], v[220:223], v[34:37]
	v_mfma_f32_16x16x32_bf16 v[22:25], v[148:151], v[228:231], v[22:25]
	v_mfma_f32_16x16x32_bf16 v[18:21], v[156:159], v[228:231], v[18:21]
	s_setprio 0
	s_setprio 1
	v_mfma_f32_16x16x32_bf16 v[46:49], v[160:163], v[176:179], v[46:49]
	v_mfma_f32_16x16x32_bf16 v[42:45], v[168:171], v[176:179], v[42:45]
	v_mfma_f32_16x16x32_bf16 v[30:33], v[160:163], v[190:193], v[30:33]
	v_mfma_f32_16x16x32_bf16 v[26:29], v[168:171], v[190:193], v[26:29]
	v_mfma_f32_16x16x32_bf16 v[14:17], v[160:163], v[216:219], v[14:17]
	v_mfma_f32_16x16x32_bf16 v[10:13], v[168:171], v[216:219], v[10:13]
	v_mfma_f32_16x16x32_bf16 v[6:9], v[160:163], v[224:227], v[6:9]
	v_mfma_f32_16x16x32_bf16 v[2:5], v[168:171], v[224:227], v[2:5]
	v_mfma_f32_16x16x32_bf16 v[46:49], v[164:167], v[186:189], v[46:49]
	v_mfma_f32_16x16x32_bf16 v[42:45], v[172:175], v[186:189], v[42:45]
	v_mfma_f32_16x16x32_bf16 v[30:33], v[164:167], v[212:215], v[30:33]
	v_mfma_f32_16x16x32_bf16 v[26:29], v[172:175], v[212:215], v[26:29]
	v_mfma_f32_16x16x32_bf16 v[14:17], v[164:167], v[220:223], v[14:17]
	v_mfma_f32_16x16x32_bf16 v[10:13], v[172:175], v[220:223], v[10:13]
	v_mfma_f32_16x16x32_bf16 v[6:9], v[164:167], v[228:231], v[6:9]
	v_mfma_f32_16x16x32_bf16 v[2:5], v[172:175], v[228:231], v[2:5]
	s_setprio 0
	s_barrier
	s_add_i32 s48, 0, 0x18000
	s_add_i32 s49, 0, 0x1c000
	v_add_u32_e32 v156, s48, v141
	v_add_u32_e32 v172, s49, v141
	ds_read_b128 v[144:147], v156
	ds_read_b128 v[148:151], v156 offset:1024
	ds_read_b128 v[152:155], v156 offset:2048
	ds_read_b128 v[156:159], v156 offset:3072
	ds_read_b128 v[160:163], v172
	ds_read_b128 v[164:167], v172 offset:1024
	ds_read_b128 v[168:171], v172 offset:2048
	ds_read_b128 v[172:175], v172 offset:3072
	s_add_u32 s22, s22, 0x40000
	s_addc_u32 s23, s23, 0
	s_mov_b32 m0, s31
	v_lshl_add_u64 v[236:237], s[22:23], 0, v[134:135]
	ds_read_b128 v[176:179], v143 offset:32768
	ds_read_b128 v[186:189], v143 offset:33792
	ds_read_b128 v[190:193], v143 offset:34816
	ds_read_b128 v[212:215], v143 offset:35840
	ds_read_b128 v[216:219], v143 offset:36864
	ds_read_b128 v[220:223], v143 offset:37888
	ds_read_b128 v[224:227], v143 offset:38912
	ds_read_b128 v[228:231], v143 offset:39936
	global_load_lds_dwordx4 v[236:237], off
	v_lshl_add_u64 v[236:237], s[22:23], 0, v[132:133]
	s_mov_b32 m0, s34
	s_nop 0
	global_load_lds_dwordx4 v[236:237], off
	s_waitcnt vmcnt(8)
	s_waitcnt lgkmcnt(0)
	s_barrier
	s_setprio 1
	s_waitcnt lgkmcnt(0)
	v_mfma_f32_16x16x32_bf16 v[126:129], v[144:147], v[176:179], v[126:129]
	v_mfma_f32_16x16x32_bf16 v[122:125], v[152:155], v[176:179], v[122:125]
	v_mfma_f32_16x16x32_bf16 v[118:121], v[144:147], v[190:193], v[118:121]
	v_mfma_f32_16x16x32_bf16 v[114:117], v[152:155], v[190:193], v[114:117]
	v_mfma_f32_16x16x32_bf16 v[102:105], v[144:147], v[216:219], v[102:105]
	v_mfma_f32_16x16x32_bf16 v[98:101], v[152:155], v[216:219], v[98:101]
	v_mfma_f32_16x16x32_bf16 v[86:89], v[144:147], v[224:227], v[86:89]
	v_mfma_f32_16x16x32_bf16 v[82:85], v[152:155], v[224:227], v[82:85]
	v_mfma_f32_16x16x32_bf16 v[126:129], v[148:151], v[186:189], v[126:129]
	v_mfma_f32_16x16x32_bf16 v[122:125], v[156:159], v[186:189], v[122:125]
	v_mfma_f32_16x16x32_bf16 v[118:121], v[148:151], v[212:215], v[118:121]
	v_mfma_f32_16x16x32_bf16 v[114:117], v[156:159], v[212:215], v[114:117]
	v_mfma_f32_16x16x32_bf16 v[102:105], v[148:151], v[220:223], v[102:105]
	v_mfma_f32_16x16x32_bf16 v[98:101], v[156:159], v[220:223], v[98:101]
	v_mfma_f32_16x16x32_bf16 v[86:89], v[148:151], v[228:231], v[86:89]
	v_mfma_f32_16x16x32_bf16 v[82:85], v[156:159], v[228:231], v[82:85]
	s_setprio 0
	s_setprio 1
	v_mfma_f32_16x16x32_bf16 v[110:113], v[160:163], v[176:179], v[110:113]
	v_mfma_f32_16x16x32_bf16 v[106:109], v[168:171], v[176:179], v[106:109]
	v_mfma_f32_16x16x32_bf16 v[94:97], v[160:163], v[190:193], v[94:97]
	v_mfma_f32_16x16x32_bf16 v[90:93], v[168:171], v[190:193], v[90:93]
	v_mfma_f32_16x16x32_bf16 v[78:81], v[160:163], v[216:219], v[78:81]
	v_mfma_f32_16x16x32_bf16 v[74:77], v[168:171], v[216:219], v[74:77]
	v_mfma_f32_16x16x32_bf16 v[70:73], v[160:163], v[224:227], v[70:73]
	v_mfma_f32_16x16x32_bf16 v[66:69], v[168:171], v[224:227], v[66:69]
	v_mfma_f32_16x16x32_bf16 v[110:113], v[164:167], v[186:189], v[110:113]
	v_mfma_f32_16x16x32_bf16 v[106:109], v[172:175], v[186:189], v[106:109]
	v_mfma_f32_16x16x32_bf16 v[94:97], v[164:167], v[212:215], v[94:97]
	v_mfma_f32_16x16x32_bf16 v[90:93], v[172:175], v[212:215], v[90:93]
	v_mfma_f32_16x16x32_bf16 v[78:81], v[164:167], v[220:223], v[78:81]
	v_mfma_f32_16x16x32_bf16 v[74:77], v[172:175], v[220:223], v[74:77]
	v_mfma_f32_16x16x32_bf16 v[70:73], v[164:167], v[228:231], v[70:73]
	v_mfma_f32_16x16x32_bf16 v[66:69], v[172:175], v[228:231], v[66:69]
	s_setprio 0
	s_barrier
	s_add_i32 s22, s48, s28
	v_lshl_add_u64 v[180:181], v[180:181], 0, s[16:17]
	s_mov_b32 m0, s22
	ds_read_b128 v[176:179], v143 offset:49152
	ds_read_b128 v[186:189], v143 offset:50176
	ds_read_b128 v[190:193], v143 offset:51200
	ds_read_b128 v[212:215], v143 offset:52224
	ds_read_b128 v[216:219], v143 offset:53248
	ds_read_b128 v[220:223], v143 offset:54272
	ds_read_b128 v[224:227], v143 offset:55296
	ds_read_b128 v[228:231], v143 offset:56320
	global_load_lds_dwordx4 v[180:181], off
	s_add_i32 m0, s22, 0x2000
	s_add_u32 s20, s20, 0x40080
	v_lshl_add_u64 v[180:181], v[194:195], 0, s[16:17]
	s_addc_u32 s21, s21, 0
	s_add_i32 s22, s49, s28
	global_load_lds_dwordx4 v[180:181], off
	v_lshl_add_u64 v[180:181], s[20:21], 0, v[0:1]
	s_mov_b32 m0, s22
	s_nop 0
	global_load_lds_dwordx4 v[180:181], off
	v_lshl_add_u64 v[180:181], s[20:21], 0, v[130:131]
	s_add_i32 m0, s22, 0x2000
	s_nop 0
	global_load_lds_dwordx4 v[180:181], off
	v_lshl_add_u64 v[180:181], v[232:233], 0, s[16:17]
	s_mov_b32 m0, s35
	s_nop 0
	global_load_lds_dwordx4 v[180:181], off
	v_lshl_add_u64 v[180:181], v[234:235], 0, s[16:17]
	s_mov_b32 m0, s36
	s_nop 0
	global_load_lds_dwordx4 v[180:181], off
	s_waitcnt vmcnt(8)
	s_waitcnt lgkmcnt(0)
	s_barrier
	s_setprio 1
	s_waitcnt lgkmcnt(0)
	v_mfma_f32_16x16x32_bf16 v[62:65], v[144:147], v[176:179], v[62:65]
	v_mfma_f32_16x16x32_bf16 v[58:61], v[152:155], v[176:179], v[58:61]
	v_mfma_f32_16x16x32_bf16 v[54:57], v[144:147], v[190:193], v[54:57]
	v_mfma_f32_16x16x32_bf16 v[50:53], v[152:155], v[190:193], v[50:53]
	v_mfma_f32_16x16x32_bf16 v[38:41], v[144:147], v[216:219], v[38:41]
	v_mfma_f32_16x16x32_bf16 v[34:37], v[152:155], v[216:219], v[34:37]
	v_mfma_f32_16x16x32_bf16 v[22:25], v[144:147], v[224:227], v[22:25]
	v_mfma_f32_16x16x32_bf16 v[18:21], v[152:155], v[224:227], v[18:21]
	v_mfma_f32_16x16x32_bf16 v[62:65], v[148:151], v[186:189], v[62:65]
	v_mfma_f32_16x16x32_bf16 v[58:61], v[156:159], v[186:189], v[58:61]
	v_mfma_f32_16x16x32_bf16 v[54:57], v[148:151], v[212:215], v[54:57]
	v_mfma_f32_16x16x32_bf16 v[50:53], v[156:159], v[212:215], v[50:53]
	v_mfma_f32_16x16x32_bf16 v[38:41], v[148:151], v[220:223], v[38:41]
	v_mfma_f32_16x16x32_bf16 v[34:37], v[156:159], v[220:223], v[34:37]
	v_mfma_f32_16x16x32_bf16 v[22:25], v[148:151], v[228:231], v[22:25]
	v_mfma_f32_16x16x32_bf16 v[18:21], v[156:159], v[228:231], v[18:21]
	s_setprio 0
	s_setprio 1
	v_mfma_f32_16x16x32_bf16 v[46:49], v[160:163], v[176:179], v[46:49]
	v_mfma_f32_16x16x32_bf16 v[42:45], v[168:171], v[176:179], v[42:45]
	v_mfma_f32_16x16x32_bf16 v[30:33], v[160:163], v[190:193], v[30:33]
	v_mfma_f32_16x16x32_bf16 v[26:29], v[168:171], v[190:193], v[26:29]
	v_mfma_f32_16x16x32_bf16 v[14:17], v[160:163], v[216:219], v[14:17]
	v_mfma_f32_16x16x32_bf16 v[10:13], v[168:171], v[216:219], v[10:13]
	v_mfma_f32_16x16x32_bf16 v[6:9], v[160:163], v[224:227], v[6:9]
	v_mfma_f32_16x16x32_bf16 v[2:5], v[168:171], v[224:227], v[2:5]
	v_mfma_f32_16x16x32_bf16 v[46:49], v[164:167], v[186:189], v[46:49]
	v_mfma_f32_16x16x32_bf16 v[42:45], v[172:175], v[186:189], v[42:45]
	v_mfma_f32_16x16x32_bf16 v[30:33], v[164:167], v[212:215], v[30:33]
	v_mfma_f32_16x16x32_bf16 v[26:29], v[172:175], v[212:215], v[26:29]
	v_mfma_f32_16x16x32_bf16 v[14:17], v[164:167], v[220:223], v[14:17]
	v_mfma_f32_16x16x32_bf16 v[10:13], v[172:175], v[220:223], v[10:13]
	v_mfma_f32_16x16x32_bf16 v[6:9], v[164:167], v[228:231], v[6:9]
	v_mfma_f32_16x16x32_bf16 v[2:5], v[172:175], v[228:231], v[2:5]
	s_setprio 0
	s_add_i32 s46, s46, 2
	s_add_u32 s18, s18, 0x100
	s_addc_u32 s19, s19, 0
	s_add_u32 s44, s44, 0x100
	s_addc_u32 s45, s45, 0
	s_add_u32 s20, s18, 0xfffc0080
	s_addc_u32 s21, s19, -1
	s_add_i32 s48, 0, 0x10000
	s_cmp_eq_u32 s46, 12
	s_cselect_b32 s23, s11, s21
	s_cselect_b32 s22, s42, s20
	s_cselect_b32 s21, s9, s45
	s_cselect_b32 s20, s43, s44
	s_add_i32 s50, 0, 0x14000
	s_cmp_gt_u32 s46, 13
	s_barrier
	s_cbranch_scc0 .LBB0_213
	s_and_b64 vcc, exec, s[6:7]
	s_cbranch_vccz .LBB0_216
	s_barrier

.LBB0_534:
	s_waitcnt lgkmcnt(14)
	v_mfma_f32_32x32x16_bf16 v[2:17], v[134:137], v[178:181], v[2:17]
	v_exp_f32_e32 v98, v98
	v_exp_f32_e32 v99, v99
	v_exp_f32_e32 v100, v100
	v_exp_f32_e32 v101, v101
	s_waitcnt lgkmcnt(12)
	v_mfma_f32_32x32x16_bf16 v[18:33], v[134:137], v[174:177], v[18:33]
	v_exp_f32_e32 v102, v102
	v_exp_f32_e32 v103, v103
	v_exp_f32_e32 v104, v104
	v_exp_f32_e32 v105, v105
	v_add_u32_e32 v78, s22, v221
	ds_read_b128 v[62:65], v78
	ds_read_b128 v[174:177], v78 offset:512
	s_waitcnt lgkmcnt(12)
	v_mfma_f32_32x32x16_bf16 v[2:17], v[126:129], v[66:69], v[2:17]
	v_exp_f32_e32 v106, v106
	v_exp_f32_e32 v107, v107
	v_exp_f32_e32 v108, v108
	v_exp_f32_e32 v109, v109
	ds_read_b128 v[178:181], v78 offset:2048
	ds_read_b128 v[170:173], v78 offset:2560
	s_waitcnt lgkmcnt(12)
	v_mfma_f32_32x32x16_bf16 v[18:33], v[126:129], v[70:73], v[18:33]
	v_exp_f32_e32 v110, v110
	v_exp_f32_e32 v111, v111
	v_exp_f32_e32 v112, v112
	v_exp_f32_e32 v113, v113
	ds_read_b128 v[166:169], v78 offset:4096
	ds_read_b128 v[162:165], v78 offset:4608
	s_waitcnt lgkmcnt(12)
	v_mfma_f32_32x32x16_bf16 v[2:17], v[118:121], v[74:77], v[2:17]
	v_exp_f32_e32 v82, v82
	v_exp_f32_e32 v83, v83
	v_exp_f32_e32 v84, v84
	v_exp_f32_e32 v85, v85
	ds_read_b128 v[158:161], v78 offset:6144
	ds_read_b128 v[154:157], v78 offset:6656
	s_waitcnt lgkmcnt(12)
	v_mfma_f32_32x32x16_bf16 v[18:33], v[118:121], v[50:53], v[18:33]
	v_exp_f32_e32 v86, v86
	v_exp_f32_e32 v87, v87
	v_exp_f32_e32 v88, v88
	v_exp_f32_e32 v89, v89
	s_waitcnt lgkmcnt(10)
	v_mfma_f32_32x32x16_bf16 v[2:17], v[114:117], v[54:57], v[2:17]
	v_exp_f32_e32 v90, v90
	v_exp_f32_e32 v91, v91
	v_exp_f32_e32 v92, v92
	v_exp_f32_e32 v93, v93
	s_waitcnt lgkmcnt(8)
	v_mfma_f32_32x32x16_bf16 v[18:33], v[114:117], v[58:61], v[18:33]
	v_exp_f32_e32 v94, v94
	v_exp_f32_e32 v95, v95
	v_exp_f32_e32 v96, v96
	v_exp_f32_e32 v97, v97
	s_andn2_b64 vcc, exec, s[4:5]
	s_add_i32 s4, s22, 0x2000
	s_cmpk_lg_i32 s22, 0x4000
	s_cselect_b32 s24, s4, 0
	s_waitcnt vmcnt(2) lgkmcnt(0)
	s_barrier
	s_cbranch_vccnz .LBB0_536
	s_waitcnt lgkmcnt(0)
	v_add_u32_e32 v66, s19, v218
	ds_read_b128 v[50:53], v66 offset:49248
	ds_read_b128 v[54:57], v66 offset:49216
	ds_read_b128 v[58:61], v66 offset:49184
	ds_read_b128 v[66:69], v66 offset:49152
	s_waitcnt lgkmcnt(3)
	v_pk_mul_f32 v[14:15], v[14:15], v[50:51]
	s_waitcnt lgkmcnt(2)
	v_pk_mul_f32 v[10:11], v[10:11], v[54:55]
	s_waitcnt lgkmcnt(1)
	v_pk_mul_f32 v[6:7], v[6:7], v[58:59]
	v_pk_mul_f32 v[16:17], v[16:17], v[52:53]
	v_pk_mul_f32 v[12:13], v[12:13], v[56:57]
	v_pk_mul_f32 v[8:9], v[8:9], v[60:61]
	s_waitcnt lgkmcnt(0)
	v_pk_mul_f32 v[4:5], v[4:5], v[68:69]
	v_pk_mul_f32 v[2:3], v[2:3], v[66:67]
	v_pk_mul_f32 v[30:31], v[30:31], v[50:51]
	v_pk_mul_f32 v[26:27], v[26:27], v[54:55]
	v_pk_mul_f32 v[22:23], v[22:23], v[58:59]
	v_pk_mul_f32 v[32:33], v[32:33], v[52:53]
	v_pk_mul_f32 v[28:29], v[28:29], v[56:57]
	v_pk_mul_f32 v[24:25], v[24:25], v[60:61]
	v_pk_mul_f32 v[20:21], v[20:21], v[68:69]
	v_pk_mul_f32 v[18:19], v[18:19], v[66:67]
.LBB0_536:
	v_add_u32_e32 v189, s23, v222
	ds_read_b64_tr_b16 v[150:151], v189 offset:24576
	ds_read_b64_tr_b16 v[152:153], v189 offset:25088
	s_waitcnt lgkmcnt(9)
	v_mfma_f32_32x32x16_bf16 v[66:81], v[62:65], v[142:145], v[34:49]
	v_add_f32_e32 v50, v98, v99
	v_add_f32_e32 v50, v100, v50
	v_add_f32_e32 v50, v101, v50
	v_add_f32_e32 v50, v102, v50
	v_add_f32_e32 v50, v103, v50
	v_cvt_pk_bf16_f32 v134, v98, v99
	v_cvt_pk_bf16_f32 v135, v100, v101
	ds_read_b64_tr_b16 v[146:147], v189 offset:28672
	ds_read_b64_tr_b16 v[148:149], v189 offset:29184
	v_add_f32_e32 v50, v104, v50
	v_add_f32_e32 v50, v105, v50
	v_add_f32_e32 v50, v106, v50
	v_add_f32_e32 v114, v107, v50
	s_waitcnt lgkmcnt(10)
	v_mfma_f32_32x32x16_bf16 v[50:65], v[174:177], v[142:145], v[34:49]
	v_cvt_pk_bf16_f32 v136, v102, v103
	v_cvt_pk_bf16_f32 v137, v104, v105
	ds_read_b64_tr_b16 v[98:99], v189 offset:25600
	ds_read_b64_tr_b16 v[100:101], v189 offset:26112
	s_waitcnt lgkmcnt(11)
	v_mfma_f32_32x32x16_bf16 v[66:81], v[178:181], v[138:141], v[66:81]
	v_add_f32_e32 v102, v108, v114
	v_add_f32_e32 v102, v109, v102
	v_add_f32_e32 v102, v110, v102
	v_add_f32_e32 v114, v111, v102
	v_cvt_pk_bf16_f32 v126, v106, v107
	v_cvt_pk_bf16_f32 v127, v108, v109
	ds_read_b64_tr_b16 v[102:103], v189 offset:29696
	ds_read_b64_tr_b16 v[104:105], v189 offset:30208
	s_waitcnt lgkmcnt(12)
	v_mfma_f32_32x32x16_bf16 v[50:65], v[170:173], v[138:141], v[50:65]
	v_add_f32_e32 v106, v112, v114
	v_add_f32_e32 v106, v113, v106
	v_add_f32_e32 v106, v82, v106
	v_add_f32_e32 v114, v83, v106
	v_cvt_pk_bf16_f32 v128, v110, v111
	v_cvt_pk_bf16_f32 v129, v112, v113
	ds_read_b64_tr_b16 v[106:107], v189 offset:26624
	ds_read_b64_tr_b16 v[108:109], v189 offset:27136
	s_waitcnt lgkmcnt(13)
	v_mfma_f32_32x32x16_bf16 v[66:81], v[166:169], v[130:133], v[66:81]
	v_add_f32_e32 v110, v84, v114
	v_add_f32_e32 v110, v85, v110
	v_add_f32_e32 v110, v86, v110
	v_add_f32_e32 v110, v87, v110
	v_cvt_pk_bf16_f32 v118, v82, v83
	v_cvt_pk_bf16_f32 v119, v84, v85
	ds_read_b64_tr_b16 v[82:83], v189 offset:30720
	ds_read_b64_tr_b16 v[84:85], v189 offset:31232
	s_waitcnt lgkmcnt(14)
	v_mfma_f32_32x32x16_bf16 v[50:65], v[162:165], v[130:133], v[50:65]
	v_add_f32_e32 v110, v88, v110
	v_add_f32_e32 v110, v89, v110
	v_add_f32_e32 v110, v90, v110
	v_add_f32_e32 v110, v91, v110
	v_cvt_pk_bf16_f32 v120, v86, v87
	v_cvt_pk_bf16_f32 v121, v88, v89
	ds_read_b64_tr_b16 v[86:87], v189 offset:27648
	ds_read_b64_tr_b16 v[88:89], v189 offset:28160
	s_waitcnt lgkmcnt(14)
	v_mfma_f32_32x32x16_bf16 v[66:81], v[158:161], v[122:125], v[66:81]
	v_add_f32_e32 v110, v92, v110
	v_add_f32_e32 v110, v93, v110
	v_add_f32_e32 v110, v94, v110
	v_add_f32_e32 v110, v95, v110
	v_cvt_pk_bf16_f32 v114, v90, v91
	v_cvt_pk_bf16_f32 v115, v92, v93
	ds_read_b64_tr_b16 v[90:91], v189 offset:31744
	ds_read_b64_tr_b16 v[92:93], v189 offset:32256
	v_mfma_f32_32x32x16_bf16 v[50:65], v[154:157], v[122:125], v[50:65]
	v_add_f32_e32 v110, v96, v110
	v_add_f32_e32 v110, v97, v110
	v_add_f32_e32 v110, 0, v110
	v_cvt_pk_bf16_f32 v116, v94, v95
	v_cvt_pk_bf16_f32 v117, v96, v97
	v_max_f32_e32 v94, v67, v67
	v_max_f32_e32 v95, v66, v66
	v_max_f32_e32 v94, v95, v94
	s_nop 3
	v_max3_f32 v95, v68, v69, v51
	v_max3_f32 v94, v94, v50, v52
	v_max3_f32 v94, v94, v53, v70
	v_max3_f32 v95, v95, v72, v73
	v_max3_f32 v94, v94, v71, v54
	v_max3_f32 v95, v95, v56, v57
	v_max3_f32 v94, v94, v55, v74
	v_max3_f32 v95, v95, v76, v77
	v_max3_f32 v94, v94, v75, v58
	v_max3_f32 v95, v95, v60, v61
	v_max3_f32 v94, v94, v59, v78
	v_max3_f32 v95, v95, v80, v81
	v_max3_f32 v94, v94, v79, v62
	v_max3_f32 v95, v95, v64, v65
	v_add_f32_e32 v223, v0, v110
	v_max3_f32 v0, v94, v63, v95
	v_mov_b32_e32 v94, v0
	s_nop 1
	v_permlane32_swap_b32_e32 v0, v94
	s_add_i32 s4, s22, s20
	s_mov_b32 s5, m0
	s_mov_b32 m0, s4
	s_nop 0
	global_load_lds_dwordx4 v[194:195], off
	s_mov_b32 m0, s5
	v_max_f32_e32 v0, v0, v94
	s_add_i32 s4, s24, s21
	s_mov_b32 s5, m0
	s_mov_b32 m0, s4
	s_nop 0
	global_load_lds_dwordx4 v[192:193], off
	s_mov_b32 m0, s5
	v_cmp_lt_f32_e32 vcc, s82, v0
	s_cmp_lg_u64 vcc, 0
	s_cselect_b64 s[4:5], -1, 0
	s_cbranch_vccnz .LBB0_544
.LBB0_537:
	s_waitcnt lgkmcnt(14)
	v_mfma_f32_32x32x16_bf16 v[2:17], v[134:137], v[150:153], v[2:17]
	v_exp_f32_e32 v66, v66
	v_exp_f32_e32 v67, v67
	v_exp_f32_e32 v68, v68
	v_exp_f32_e32 v69, v69
	s_waitcnt lgkmcnt(12)
	v_mfma_f32_32x32x16_bf16 v[18:33], v[134:137], v[146:149], v[18:33]
	v_exp_f32_e32 v70, v70
	v_exp_f32_e32 v71, v71
	v_exp_f32_e32 v72, v72
	v_exp_f32_e32 v73, v73
	v_add_u32_e32 v0, s24, v221
	ds_read_b128 v[174:177], v0
	ds_read_b128 v[170:173], v0 offset:512
	s_waitcnt lgkmcnt(12)
	v_mfma_f32_32x32x16_bf16 v[2:17], v[126:129], v[98:101], v[2:17]
	v_exp_f32_e32 v74, v74
	v_exp_f32_e32 v75, v75
	v_exp_f32_e32 v76, v76
	v_exp_f32_e32 v77, v77
	ds_read_b128 v[166:169], v0 offset:2048
	ds_read_b128 v[162:165], v0 offset:2560
	s_waitcnt lgkmcnt(12)
	v_mfma_f32_32x32x16_bf16 v[18:33], v[126:129], v[102:105], v[18:33]
	v_exp_f32_e32 v78, v78
	v_exp_f32_e32 v79, v79
	v_exp_f32_e32 v80, v80
	v_exp_f32_e32 v81, v81
	ds_read_b128 v[158:161], v0 offset:4096
	ds_read_b128 v[154:157], v0 offset:4608
	s_waitcnt lgkmcnt(12)
	v_mfma_f32_32x32x16_bf16 v[2:17], v[118:121], v[106:109], v[2:17]
	v_exp_f32_e32 v50, v50
	v_exp_f32_e32 v51, v51
	v_exp_f32_e32 v52, v52
	v_exp_f32_e32 v53, v53
	ds_read_b128 v[150:153], v0 offset:6144
	ds_read_b128 v[146:149], v0 offset:6656
	s_waitcnt lgkmcnt(12)
	v_mfma_f32_32x32x16_bf16 v[18:33], v[118:121], v[82:85], v[18:33]
	v_exp_f32_e32 v54, v54
	v_exp_f32_e32 v55, v55
	v_exp_f32_e32 v56, v56
	v_exp_f32_e32 v57, v57
	s_waitcnt lgkmcnt(10)
	v_mfma_f32_32x32x16_bf16 v[2:17], v[114:117], v[86:89], v[2:17]
	v_exp_f32_e32 v58, v58
	v_exp_f32_e32 v59, v59
	v_exp_f32_e32 v60, v60
	v_exp_f32_e32 v61, v61
	s_waitcnt lgkmcnt(8)
	v_mfma_f32_32x32x16_bf16 v[18:33], v[114:117], v[90:93], v[18:33]
	v_exp_f32_e32 v62, v62
	v_exp_f32_e32 v63, v63
	v_exp_f32_e32 v64, v64
	v_exp_f32_e32 v65, v65
	s_andn2_b64 vcc, exec, s[4:5]
	s_add_i32 s4, s24, 0x2000
	s_cmpk_lg_i32 s24, 0x4000
	s_cselect_b32 s5, s4, 0
	s_add_i32 s11, s11, 2
	v_lshl_add_u64 v[192:193], v[192:193], 0, s[90:91]
	v_lshl_add_u64 v[194:195], v[194:195], 0, s[90:91]
	s_cmpk_gt_u32 s11, 0x7c
	s_waitcnt vmcnt(2) lgkmcnt(0)
	s_barrier
	s_cbranch_vccnz .LBB0_539
	s_waitcnt lgkmcnt(0)
	v_add_u32_e32 v0, s19, v218
	ds_read_b128 v[82:85], v0 offset:49248
	ds_read_b128 v[86:89], v0 offset:49216
	ds_read_b128 v[90:93], v0 offset:49152
	ds_read_b128 v[94:97], v0 offset:49184
	s_waitcnt lgkmcnt(3)
	v_pk_mul_f32 v[16:17], v[16:17], v[84:85]
	v_pk_mul_f32 v[14:15], v[14:15], v[82:83]
	s_waitcnt lgkmcnt(2)
	v_pk_mul_f32 v[12:13], v[12:13], v[88:89]
	v_pk_mul_f32 v[10:11], v[10:11], v[86:87]
	s_waitcnt lgkmcnt(0)
	v_pk_mul_f32 v[8:9], v[8:9], v[96:97]
	v_pk_mul_f32 v[6:7], v[6:7], v[94:95]
	v_pk_mul_f32 v[4:5], v[4:5], v[92:93]
	v_pk_mul_f32 v[2:3], v[2:3], v[90:91]
	v_pk_mul_f32 v[32:33], v[32:33], v[84:85]
	v_pk_mul_f32 v[30:31], v[30:31], v[82:83]
	v_pk_mul_f32 v[28:29], v[28:29], v[88:89]
	v_pk_mul_f32 v[26:27], v[26:27], v[86:87]
	v_pk_mul_f32 v[24:25], v[24:25], v[96:97]
	v_pk_mul_f32 v[22:23], v[22:23], v[94:95]
	v_pk_mul_f32 v[20:21], v[20:21], v[92:93]
	v_pk_mul_f32 v[18:19], v[18:19], v[90:91]
.LBB0_539:
	s_cbranch_scc1 .LBB0_548
	s_mov_b32 s4, s22
	s_mov_b32 s23, s24
	s_mov_b32 s22, s5
	s_branch .LBB0_533

.LBB0_683:
	s_ashr_i32 s11, s10, 31
	s_lshl_b64 s[12:13], s[10:11], 19
	s_add_u32 s12, s27, s12
	s_addc_u32 s13, s28, s13
	s_and_b64 s[14:15], s[40:41], exec
	s_cselect_b32 s11, s13, s21
	s_cselect_b32 s48, s12, s20
	s_ashr_i32 s9, s8, 31
	s_lshl_b64 s[14:15], s[8:9], 19
	s_add_u32 s14, s29, s14
	s_addc_u32 s15, s30, s15
	s_and_b64 s[24:25], s[40:41], exec
	s_cselect_b32 s9, s15, s23
	s_cselect_b32 s49, s14, s22
	s_add_u32 s20, s20, 0x40080
	s_addc_u32 s21, s21, 0
	s_add_u32 s50, s22, 0x100
	v_mov_b32_e32 v2, 0
	s_addc_u32 s51, s23, 0
	s_mov_b32 s52, -2
	v_mov_b32_e32 v3, v2
	v_mov_b32_e32 v4, v2
	v_mov_b32_e32 v5, v2
	v_mov_b32_e32 v6, v2
	v_mov_b32_e32 v7, v2
	v_mov_b32_e32 v8, v2
	v_mov_b32_e32 v9, v2
	v_mov_b32_e32 v18, v2
	v_mov_b32_e32 v19, v2
	v_mov_b32_e32 v20, v2
	v_mov_b32_e32 v21, v2
	v_mov_b32_e32 v22, v2
	v_mov_b32_e32 v23, v2
	v_mov_b32_e32 v24, v2
	v_mov_b32_e32 v25, v2
	v_mov_b32_e32 v34, v2
	v_mov_b32_e32 v35, v2
	v_mov_b32_e32 v36, v2
	v_mov_b32_e32 v37, v2
	v_mov_b32_e32 v38, v2
	v_mov_b32_e32 v39, v2
	v_mov_b32_e32 v40, v2
	v_mov_b32_e32 v41, v2
	v_mov_b32_e32 v50, v2
	v_mov_b32_e32 v51, v2
	v_mov_b32_e32 v52, v2
	v_mov_b32_e32 v53, v2
	v_mov_b32_e32 v54, v2
	v_mov_b32_e32 v55, v2
	v_mov_b32_e32 v56, v2
	v_mov_b32_e32 v57, v2
	v_mov_b32_e32 v10, v2
	v_mov_b32_e32 v11, v2
	v_mov_b32_e32 v12, v2
	v_mov_b32_e32 v13, v2
	v_mov_b32_e32 v14, v2
	v_mov_b32_e32 v15, v2
	v_mov_b32_e32 v16, v2
	v_mov_b32_e32 v17, v2
	v_mov_b32_e32 v26, v2
	v_mov_b32_e32 v27, v2
	v_mov_b32_e32 v28, v2
	v_mov_b32_e32 v29, v2
	v_mov_b32_e32 v30, v2
	v_mov_b32_e32 v31, v2
	v_mov_b32_e32 v32, v2
	v_mov_b32_e32 v33, v2
	v_mov_b32_e32 v42, v2
	v_mov_b32_e32 v43, v2
	v_mov_b32_e32 v44, v2
	v_mov_b32_e32 v45, v2
	v_mov_b32_e32 v46, v2
	v_mov_b32_e32 v47, v2
	v_mov_b32_e32 v48, v2
	v_mov_b32_e32 v49, v2
	v_mov_b32_e32 v58, v2
	v_mov_b32_e32 v59, v2
	v_mov_b32_e32 v60, v2
	v_mov_b32_e32 v61, v2
	v_mov_b32_e32 v62, v2
	v_mov_b32_e32 v63, v2
	v_mov_b32_e32 v64, v2
	v_mov_b32_e32 v65, v2
	v_mov_b32_e32 v66, v2
	v_mov_b32_e32 v67, v2
	v_mov_b32_e32 v68, v2
	v_mov_b32_e32 v69, v2
	v_mov_b32_e32 v70, v2
	v_mov_b32_e32 v71, v2
	v_mov_b32_e32 v72, v2
	v_mov_b32_e32 v73, v2
	v_mov_b32_e32 v82, v2
	v_mov_b32_e32 v83, v2
	v_mov_b32_e32 v84, v2
	v_mov_b32_e32 v85, v2
	v_mov_b32_e32 v86, v2
	v_mov_b32_e32 v87, v2
	v_mov_b32_e32 v88, v2
	v_mov_b32_e32 v89, v2
	v_mov_b32_e32 v98, v2
	v_mov_b32_e32 v99, v2
	v_mov_b32_e32 v100, v2
	v_mov_b32_e32 v101, v2
	v_mov_b32_e32 v102, v2
	v_mov_b32_e32 v103, v2
	v_mov_b32_e32 v104, v2
	v_mov_b32_e32 v105, v2
	v_mov_b32_e32 v114, v2
	v_mov_b32_e32 v115, v2
	v_mov_b32_e32 v116, v2
	v_mov_b32_e32 v117, v2
	v_mov_b32_e32 v118, v2
	v_mov_b32_e32 v119, v2
	v_mov_b32_e32 v120, v2
	v_mov_b32_e32 v121, v2
	v_mov_b32_e32 v74, v2
	v_mov_b32_e32 v75, v2
	v_mov_b32_e32 v76, v2
	v_mov_b32_e32 v77, v2
	v_mov_b32_e32 v78, v2
	v_mov_b32_e32 v79, v2
	v_mov_b32_e32 v80, v2
	v_mov_b32_e32 v81, v2
	v_mov_b32_e32 v90, v2
	v_mov_b32_e32 v91, v2
	v_mov_b32_e32 v92, v2
	v_mov_b32_e32 v93, v2
	v_mov_b32_e32 v94, v2
	v_mov_b32_e32 v95, v2
	v_mov_b32_e32 v96, v2
	v_mov_b32_e32 v97, v2
	v_mov_b32_e32 v106, v2
	v_mov_b32_e32 v107, v2
	v_mov_b32_e32 v108, v2
	v_mov_b32_e32 v109, v2
	v_mov_b32_e32 v110, v2
	v_mov_b32_e32 v111, v2
	v_mov_b32_e32 v112, v2
	v_mov_b32_e32 v113, v2
	v_mov_b32_e32 v122, v2
	v_mov_b32_e32 v123, v2
	v_mov_b32_e32 v124, v2
	v_mov_b32_e32 v125, v2
	v_mov_b32_e32 v126, v2
	v_mov_b32_e32 v127, v2
	v_mov_b32_e32 v128, v2
	v_mov_b32_e32 v129, v2
	s_add_u32 s22, s20, 0xfffc0080
	s_addc_u32 s23, s21, -1
	s_add_i32 s53, 0, 0x10000
	s_cmp_eq_u32 s52, 12
	s_cselect_b32 s25, s11, s23
	s_cselect_b32 s24, s48, s22
	s_cselect_b32 s23, s9, s51
	s_cselect_b32 s22, s49, s50
	s_add_i32 s56, 0, 0x14000
.LBB0_684:
	v_add_u32_e32 v156, s53, v145
	v_add_u32_e32 v172, s56, v145
	ds_read_b128 v[140:143], v156
	ds_read_b128 v[148:151], v156 offset:1024
	ds_read_b128 v[152:155], v156 offset:2048
	ds_read_b128 v[156:159], v156 offset:3072
	ds_read_b128 v[160:163], v172
	ds_read_b128 v[164:167], v172 offset:1024
	ds_read_b128 v[168:171], v172 offset:2048
	ds_read_b128 v[172:175], v172 offset:3072
	v_lshl_add_u64 v[180:181], s[20:21], 0, v[136:137]
	s_add_i32 m0, s35, 0xc000
	ds_read_b128 v[176:179], v147
	ds_read_b128 v[186:189], v147 offset:1024
	ds_read_b128 v[190:193], v147 offset:2048
	ds_read_b128 v[212:215], v147 offset:3072
	ds_read_b128 v[216:219], v147 offset:4096
	ds_read_b128 v[220:223], v147 offset:5120
	ds_read_b128 v[224:227], v147 offset:6144
	ds_read_b128 v[228:231], v147 offset:7168
	global_load_lds_dwordx4 v[180:181], off
	v_lshl_add_u64 v[180:181], s[20:21], 0, v[138:139]
	s_add_i32 m0, s35, 0xe000
	s_nop 0
	global_load_lds_dwordx4 v[180:181], off
	s_waitcnt vmcnt(8)
	s_waitcnt lgkmcnt(0)
	s_barrier
	s_setprio 1
	s_waitcnt lgkmcnt(0)
	v_mfma_f32_16x16x32_bf16 v[126:129], v[140:143], v[176:179], v[126:129]
	v_mfma_f32_16x16x32_bf16 v[122:125], v[152:155], v[176:179], v[122:125]
	v_mfma_f32_16x16x32_bf16 v[110:113], v[140:143], v[190:193], v[110:113]
	v_mfma_f32_16x16x32_bf16 v[106:109], v[152:155], v[190:193], v[106:109]
	v_mfma_f32_16x16x32_bf16 v[94:97], v[140:143], v[216:219], v[94:97]
	v_mfma_f32_16x16x32_bf16 v[90:93], v[152:155], v[216:219], v[90:93]
	v_mfma_f32_16x16x32_bf16 v[78:81], v[140:143], v[224:227], v[78:81]
	v_mfma_f32_16x16x32_bf16 v[74:77], v[152:155], v[224:227], v[74:77]
	v_mfma_f32_16x16x32_bf16 v[126:129], v[148:151], v[186:189], v[126:129]
	v_mfma_f32_16x16x32_bf16 v[122:125], v[156:159], v[186:189], v[122:125]
	v_mfma_f32_16x16x32_bf16 v[110:113], v[148:151], v[212:215], v[110:113]
	v_mfma_f32_16x16x32_bf16 v[106:109], v[156:159], v[212:215], v[106:109]
	v_mfma_f32_16x16x32_bf16 v[94:97], v[148:151], v[220:223], v[94:97]
	v_mfma_f32_16x16x32_bf16 v[90:93], v[156:159], v[220:223], v[90:93]
	v_mfma_f32_16x16x32_bf16 v[78:81], v[148:151], v[228:231], v[78:81]
	v_mfma_f32_16x16x32_bf16 v[74:77], v[156:159], v[228:231], v[74:77]
	s_setprio 0
	s_setprio 1
	v_mfma_f32_16x16x32_bf16 v[118:121], v[160:163], v[176:179], v[118:121]
	v_mfma_f32_16x16x32_bf16 v[114:117], v[168:171], v[176:179], v[114:117]
	v_mfma_f32_16x16x32_bf16 v[102:105], v[160:163], v[190:193], v[102:105]
	v_mfma_f32_16x16x32_bf16 v[98:101], v[168:171], v[190:193], v[98:101]
	v_mfma_f32_16x16x32_bf16 v[86:89], v[160:163], v[216:219], v[86:89]
	v_mfma_f32_16x16x32_bf16 v[82:85], v[168:171], v[216:219], v[82:85]
	v_mfma_f32_16x16x32_bf16 v[70:73], v[160:163], v[224:227], v[70:73]
	v_mfma_f32_16x16x32_bf16 v[66:69], v[168:171], v[224:227], v[66:69]
	v_mfma_f32_16x16x32_bf16 v[118:121], v[164:167], v[186:189], v[118:121]
	v_mfma_f32_16x16x32_bf16 v[114:117], v[172:175], v[186:189], v[114:117]
	v_mfma_f32_16x16x32_bf16 v[102:105], v[164:167], v[212:215], v[102:105]
	v_mfma_f32_16x16x32_bf16 v[98:101], v[172:175], v[212:215], v[98:101]
	v_mfma_f32_16x16x32_bf16 v[86:89], v[164:167], v[220:223], v[86:89]
	v_mfma_f32_16x16x32_bf16 v[82:85], v[172:175], v[220:223], v[82:85]
	v_mfma_f32_16x16x32_bf16 v[70:73], v[164:167], v[228:231], v[70:73]
	v_mfma_f32_16x16x32_bf16 v[66:69], v[172:175], v[228:231], v[66:69]
	s_setprio 0
	s_barrier
	s_add_i32 s53, s53, s31
	v_lshl_add_u64 v[180:181], s[22:23], 0, v[0:1]
	s_mov_b32 m0, s53
	ds_read_b128 v[176:179], v147 offset:16384
	ds_read_b128 v[186:189], v147 offset:17408
	ds_read_b128 v[190:193], v147 offset:18432
	ds_read_b128 v[212:215], v147 offset:19456
	ds_read_b128 v[216:219], v147 offset:20480
	ds_read_b128 v[220:223], v147 offset:21504
	ds_read_b128 v[224:227], v147 offset:22528
	ds_read_b128 v[228:231], v147 offset:23552
	global_load_lds_dwordx4 v[180:181], off
	s_add_i32 m0, s53, 0x2000
	s_add_u32 s54, s22, 0x40000
	v_lshl_add_u64 v[194:195], s[22:23], 0, v[134:135]
	s_addc_u32 s55, s23, 0
	s_add_i32 s53, s56, s31
	global_load_lds_dwordx4 v[194:195], off
	v_lshl_add_u64 v[232:233], s[54:55], 0, v[0:1]
	s_mov_b32 m0, s53
	v_lshl_add_u64 v[234:235], s[24:25], 0, v[132:133]
	global_load_lds_dwordx4 v[232:233], off
	v_lshl_add_u64 v[232:233], s[54:55], 0, v[134:135]
	s_add_i32 m0, s53, 0x2000
	s_nop 0
	global_load_lds_dwordx4 v[232:233], off
	v_lshl_add_u64 v[232:233], s[24:25], 0, v[130:131]
	s_mov_b32 m0, s35
	s_nop 0
	global_load_lds_dwordx4 v[232:233], off
	s_mov_b32 m0, s36
	s_nop 0
	global_load_lds_dwordx4 v[234:235], off
	s_waitcnt vmcnt(8)
	s_waitcnt lgkmcnt(0)
	s_barrier
	s_setprio 1
	s_waitcnt lgkmcnt(0)
	v_mfma_f32_16x16x32_bf16 v[62:65], v[140:143], v[176:179], v[62:65]
	v_mfma_f32_16x16x32_bf16 v[58:61], v[152:155], v[176:179], v[58:61]
	v_mfma_f32_16x16x32_bf16 v[46:49], v[140:143], v[190:193], v[46:49]
	v_mfma_f32_16x16x32_bf16 v[42:45], v[152:155], v[190:193], v[42:45]
	v_mfma_f32_16x16x32_bf16 v[30:33], v[140:143], v[216:219], v[30:33]
	v_mfma_f32_16x16x32_bf16 v[26:29], v[152:155], v[216:219], v[26:29]
	v_mfma_f32_16x16x32_bf16 v[14:17], v[140:143], v[224:227], v[14:17]
	v_mfma_f32_16x16x32_bf16 v[10:13], v[152:155], v[224:227], v[10:13]
	v_mfma_f32_16x16x32_bf16 v[62:65], v[148:151], v[186:189], v[62:65]
	v_mfma_f32_16x16x32_bf16 v[58:61], v[156:159], v[186:189], v[58:61]
	v_mfma_f32_16x16x32_bf16 v[46:49], v[148:151], v[212:215], v[46:49]
	v_mfma_f32_16x16x32_bf16 v[42:45], v[156:159], v[212:215], v[42:45]
	v_mfma_f32_16x16x32_bf16 v[30:33], v[148:151], v[220:223], v[30:33]
	v_mfma_f32_16x16x32_bf16 v[26:29], v[156:159], v[220:223], v[26:29]
	v_mfma_f32_16x16x32_bf16 v[14:17], v[148:151], v[228:231], v[14:17]
	v_mfma_f32_16x16x32_bf16 v[10:13], v[156:159], v[228:231], v[10:13]
	s_setprio 0
	s_setprio 1
	v_mfma_f32_16x16x32_bf16 v[54:57], v[160:163], v[176:179], v[54:57]
	v_mfma_f32_16x16x32_bf16 v[50:53], v[168:171], v[176:179], v[50:53]
	v_mfma_f32_16x16x32_bf16 v[38:41], v[160:163], v[190:193], v[38:41]
	v_mfma_f32_16x16x32_bf16 v[34:37], v[168:171], v[190:193], v[34:37]
	v_mfma_f32_16x16x32_bf16 v[22:25], v[160:163], v[216:219], v[22:25]
	v_mfma_f32_16x16x32_bf16 v[18:21], v[168:171], v[216:219], v[18:21]
	v_mfma_f32_16x16x32_bf16 v[6:9], v[160:163], v[224:227], v[6:9]
	v_mfma_f32_16x16x32_bf16 v[2:5], v[168:171], v[224:227], v[2:5]
	v_mfma_f32_16x16x32_bf16 v[54:57], v[164:167], v[186:189], v[54:57]
	v_mfma_f32_16x16x32_bf16 v[50:53], v[172:175], v[186:189], v[50:53]
	v_mfma_f32_16x16x32_bf16 v[38:41], v[164:167], v[212:215], v[38:41]
	v_mfma_f32_16x16x32_bf16 v[34:37], v[172:175], v[212:215], v[34:37]
	v_mfma_f32_16x16x32_bf16 v[22:25], v[164:167], v[220:223], v[22:25]
	v_mfma_f32_16x16x32_bf16 v[18:21], v[172:175], v[220:223], v[18:21]
	v_mfma_f32_16x16x32_bf16 v[6:9], v[164:167], v[228:231], v[6:9]
	v_mfma_f32_16x16x32_bf16 v[2:5], v[172:175], v[228:231], v[2:5]
	s_setprio 0
	s_barrier
	s_add_i32 s53, 0, 0x18000
	s_add_i32 s54, 0, 0x1c000
	v_add_u32_e32 v156, s53, v145
	v_add_u32_e32 v172, s54, v145
	ds_read_b128 v[140:143], v156
	ds_read_b128 v[148:151], v156 offset:1024
	ds_read_b128 v[152:155], v156 offset:2048
	ds_read_b128 v[156:159], v156 offset:3072
	ds_read_b128 v[160:163], v172
	ds_read_b128 v[164:167], v172 offset:1024
	ds_read_b128 v[168:171], v172 offset:2048
	ds_read_b128 v[172:175], v172 offset:3072
	s_add_u32 s24, s24, 0x40000
	s_addc_u32 s25, s25, 0
	s_mov_b32 m0, s37
	v_lshl_add_u64 v[236:237], s[24:25], 0, v[130:131]
	ds_read_b128 v[176:179], v147 offset:32768
	ds_read_b128 v[186:189], v147 offset:33792
	ds_read_b128 v[190:193], v147 offset:34816
	ds_read_b128 v[212:215], v147 offset:35840
	ds_read_b128 v[216:219], v147 offset:36864
	ds_read_b128 v[220:223], v147 offset:37888
	ds_read_b128 v[224:227], v147 offset:38912
	ds_read_b128 v[228:231], v147 offset:39936
	global_load_lds_dwordx4 v[236:237], off
	v_lshl_add_u64 v[236:237], s[24:25], 0, v[132:133]
	s_mov_b32 m0, s42
	s_nop 0
	global_load_lds_dwordx4 v[236:237], off
	s_waitcnt vmcnt(8)
	s_waitcnt lgkmcnt(0)
	s_barrier
	s_setprio 1
	s_waitcnt lgkmcnt(0)
	v_mfma_f32_16x16x32_bf16 v[126:129], v[140:143], v[176:179], v[126:129]
	v_mfma_f32_16x16x32_bf16 v[122:125], v[152:155], v[176:179], v[122:125]
	v_mfma_f32_16x16x32_bf16 v[110:113], v[140:143], v[190:193], v[110:113]
	v_mfma_f32_16x16x32_bf16 v[106:109], v[152:155], v[190:193], v[106:109]
	v_mfma_f32_16x16x32_bf16 v[94:97], v[140:143], v[216:219], v[94:97]
	v_mfma_f32_16x16x32_bf16 v[90:93], v[152:155], v[216:219], v[90:93]
	v_mfma_f32_16x16x32_bf16 v[78:81], v[140:143], v[224:227], v[78:81]
	v_mfma_f32_16x16x32_bf16 v[74:77], v[152:155], v[224:227], v[74:77]
	v_mfma_f32_16x16x32_bf16 v[126:129], v[148:151], v[186:189], v[126:129]
	v_mfma_f32_16x16x32_bf16 v[122:125], v[156:159], v[186:189], v[122:125]
	v_mfma_f32_16x16x32_bf16 v[110:113], v[148:151], v[212:215], v[110:113]
	v_mfma_f32_16x16x32_bf16 v[106:109], v[156:159], v[212:215], v[106:109]
	v_mfma_f32_16x16x32_bf16 v[94:97], v[148:151], v[220:223], v[94:97]
	v_mfma_f32_16x16x32_bf16 v[90:93], v[156:159], v[220:223], v[90:93]
	v_mfma_f32_16x16x32_bf16 v[78:81], v[148:151], v[228:231], v[78:81]
	v_mfma_f32_16x16x32_bf16 v[74:77], v[156:159], v[228:231], v[74:77]
	s_setprio 0
	s_setprio 1
	v_mfma_f32_16x16x32_bf16 v[118:121], v[160:163], v[176:179], v[118:121]
	v_mfma_f32_16x16x32_bf16 v[114:117], v[168:171], v[176:179], v[114:117]
	v_mfma_f32_16x16x32_bf16 v[102:105], v[160:163], v[190:193], v[102:105]
	v_mfma_f32_16x16x32_bf16 v[98:101], v[168:171], v[190:193], v[98:101]
	v_mfma_f32_16x16x32_bf16 v[86:89], v[160:163], v[216:219], v[86:89]
	v_mfma_f32_16x16x32_bf16 v[82:85], v[168:171], v[216:219], v[82:85]
	v_mfma_f32_16x16x32_bf16 v[70:73], v[160:163], v[224:227], v[70:73]
	v_mfma_f32_16x16x32_bf16 v[66:69], v[168:171], v[224:227], v[66:69]
	v_mfma_f32_16x16x32_bf16 v[118:121], v[164:167], v[186:189], v[118:121]
	v_mfma_f32_16x16x32_bf16 v[114:117], v[172:175], v[186:189], v[114:117]
	v_mfma_f32_16x16x32_bf16 v[102:105], v[164:167], v[212:215], v[102:105]
	v_mfma_f32_16x16x32_bf16 v[98:101], v[172:175], v[212:215], v[98:101]
	v_mfma_f32_16x16x32_bf16 v[86:89], v[164:167], v[220:223], v[86:89]
	v_mfma_f32_16x16x32_bf16 v[82:85], v[172:175], v[220:223], v[82:85]
	v_mfma_f32_16x16x32_bf16 v[70:73], v[164:167], v[228:231], v[70:73]
	v_mfma_f32_16x16x32_bf16 v[66:69], v[172:175], v[228:231], v[66:69]
	s_setprio 0
	s_barrier
	s_add_i32 s24, s53, s31
	v_lshl_add_u64 v[180:181], v[180:181], 0, s[16:17]
	s_mov_b32 m0, s24
	ds_read_b128 v[176:179], v147 offset:49152
	ds_read_b128 v[186:189], v147 offset:50176
	ds_read_b128 v[190:193], v147 offset:51200
	ds_read_b128 v[212:215], v147 offset:52224
	ds_read_b128 v[216:219], v147 offset:53248
	ds_read_b128 v[220:223], v147 offset:54272
	ds_read_b128 v[224:227], v147 offset:55296
	ds_read_b128 v[228:231], v147 offset:56320
	global_load_lds_dwordx4 v[180:181], off
	s_add_i32 m0, s24, 0x2000
	s_add_u32 s22, s22, 0x40080
	v_lshl_add_u64 v[180:181], v[194:195], 0, s[16:17]
	s_addc_u32 s23, s23, 0
	s_add_i32 s24, s54, s31
	global_load_lds_dwordx4 v[180:181], off
	v_lshl_add_u64 v[180:181], s[22:23], 0, v[0:1]
	s_mov_b32 m0, s24
	s_nop 0
	global_load_lds_dwordx4 v[180:181], off
	v_lshl_add_u64 v[180:181], s[22:23], 0, v[134:135]
	s_add_i32 m0, s24, 0x2000
	s_nop 0
	global_load_lds_dwordx4 v[180:181], off
	v_lshl_add_u64 v[180:181], v[232:233], 0, s[16:17]
	s_mov_b32 m0, s43
	s_nop 0
	global_load_lds_dwordx4 v[180:181], off
	v_lshl_add_u64 v[180:181], v[234:235], 0, s[16:17]
	s_mov_b32 m0, s44
	s_nop 0
	global_load_lds_dwordx4 v[180:181], off
	s_waitcnt vmcnt(8)
	s_waitcnt lgkmcnt(0)
	s_barrier
	s_setprio 1
	s_waitcnt lgkmcnt(0)
	v_mfma_f32_16x16x32_bf16 v[62:65], v[140:143], v[176:179], v[62:65]
	v_mfma_f32_16x16x32_bf16 v[58:61], v[152:155], v[176:179], v[58:61]
	v_mfma_f32_16x16x32_bf16 v[46:49], v[140:143], v[190:193], v[46:49]
	v_mfma_f32_16x16x32_bf16 v[42:45], v[152:155], v[190:193], v[42:45]
	v_mfma_f32_16x16x32_bf16 v[30:33], v[140:143], v[216:219], v[30:33]
	v_mfma_f32_16x16x32_bf16 v[26:29], v[152:155], v[216:219], v[26:29]
	v_mfma_f32_16x16x32_bf16 v[14:17], v[140:143], v[224:227], v[14:17]
	v_mfma_f32_16x16x32_bf16 v[10:13], v[152:155], v[224:227], v[10:13]
	v_mfma_f32_16x16x32_bf16 v[62:65], v[148:151], v[186:189], v[62:65]
	v_mfma_f32_16x16x32_bf16 v[58:61], v[156:159], v[186:189], v[58:61]
	v_mfma_f32_16x16x32_bf16 v[46:49], v[148:151], v[212:215], v[46:49]
	v_mfma_f32_16x16x32_bf16 v[42:45], v[156:159], v[212:215], v[42:45]
	v_mfma_f32_16x16x32_bf16 v[30:33], v[148:151], v[220:223], v[30:33]
	v_mfma_f32_16x16x32_bf16 v[26:29], v[156:159], v[220:223], v[26:29]
	v_mfma_f32_16x16x32_bf16 v[14:17], v[148:151], v[228:231], v[14:17]
	v_mfma_f32_16x16x32_bf16 v[10:13], v[156:159], v[228:231], v[10:13]
	s_setprio 0
	s_setprio 1
	v_mfma_f32_16x16x32_bf16 v[54:57], v[160:163], v[176:179], v[54:57]
	v_mfma_f32_16x16x32_bf16 v[50:53], v[168:171], v[176:179], v[50:53]
	v_mfma_f32_16x16x32_bf16 v[38:41], v[160:163], v[190:193], v[38:41]
	v_mfma_f32_16x16x32_bf16 v[34:37], v[168:171], v[190:193], v[34:37]
	v_mfma_f32_16x16x32_bf16 v[22:25], v[160:163], v[216:219], v[22:25]
	v_mfma_f32_16x16x32_bf16 v[18:21], v[168:171], v[216:219], v[18:21]
	v_mfma_f32_16x16x32_bf16 v[6:9], v[160:163], v[224:227], v[6:9]
	v_mfma_f32_16x16x32_bf16 v[2:5], v[168:171], v[224:227], v[2:5]
	v_mfma_f32_16x16x32_bf16 v[54:57], v[164:167], v[186:189], v[54:57]
	v_mfma_f32_16x16x32_bf16 v[50:53], v[172:175], v[186:189], v[50:53]
	v_mfma_f32_16x16x32_bf16 v[38:41], v[164:167], v[212:215], v[38:41]
	v_mfma_f32_16x16x32_bf16 v[34:37], v[172:175], v[212:215], v[34:37]
	v_mfma_f32_16x16x32_bf16 v[22:25], v[164:167], v[220:223], v[22:25]
	v_mfma_f32_16x16x32_bf16 v[18:21], v[172:175], v[220:223], v[18:21]
	v_mfma_f32_16x16x32_bf16 v[6:9], v[164:167], v[228:231], v[6:9]
	v_mfma_f32_16x16x32_bf16 v[2:5], v[172:175], v[228:231], v[2:5]
	s_setprio 0
	s_add_i32 s52, s52, 2
	s_add_u32 s20, s20, 0x100
	s_addc_u32 s21, s21, 0
	s_add_u32 s50, s50, 0x100
	s_addc_u32 s51, s51, 0
	s_add_u32 s22, s20, 0xfffc0080
	s_addc_u32 s23, s21, -1
	s_add_i32 s53, 0, 0x10000
	s_cmp_eq_u32 s52, 12
	s_cselect_b32 s25, s11, s23
	s_cselect_b32 s24, s48, s22
	s_cselect_b32 s23, s9, s51
	s_cselect_b32 s22, s49, s50
	s_add_i32 s56, 0, 0x14000
	s_cmp_gt_u32 s52, 13
	s_barrier
	s_cbranch_scc0 .LBB0_684
	s_and_b64 vcc, exec, s[6:7]
	s_cbranch_vccz .LBB0_687
	s_barrier

.LBB0_1026:
	s_ashr_i32 s13, s12, 31
	s_lshl_b64 s[20:21], s[12:13], 19
	s_add_u32 s20, s37, s20
	s_addc_u32 s21, s48, s21
	s_and_b64 s[22:23], s[44:45], exec
	s_cselect_b32 s13, s21, s25
	s_cselect_b32 s15, s20, s24
	s_ashr_i32 s11, s10, 31
	s_lshl_b64 s[22:23], s[10:11], 19
	s_add_u32 s22, s49, s22
	s_addc_u32 s23, s50, s23
	s_and_b64 s[28:29], s[44:45], exec
	s_cselect_b32 s11, s23, s27
	s_cselect_b32 s59, s22, s26
	s_add_u32 s24, s24, 0x40080
	s_addc_u32 s25, s25, 0
	s_add_u32 s60, s26, 0x100
	v_mov_b32_e32 v2, 0
	s_addc_u32 s61, s27, 0
	s_mov_b32 s62, -2
	v_mov_b32_e32 v3, v2
	v_mov_b32_e32 v4, v2
	v_mov_b32_e32 v5, v2
	v_mov_b32_e32 v6, v2
	v_mov_b32_e32 v7, v2
	v_mov_b32_e32 v8, v2
	v_mov_b32_e32 v9, v2
	v_mov_b32_e32 v14, v2
	v_mov_b32_e32 v15, v2
	v_mov_b32_e32 v16, v2
	v_mov_b32_e32 v17, v2
	v_mov_b32_e32 v22, v2
	v_mov_b32_e32 v23, v2
	v_mov_b32_e32 v24, v2
	v_mov_b32_e32 v25, v2
	v_mov_b32_e32 v30, v2
	v_mov_b32_e32 v31, v2
	v_mov_b32_e32 v32, v2
	v_mov_b32_e32 v33, v2
	v_mov_b32_e32 v38, v2
	v_mov_b32_e32 v39, v2
	v_mov_b32_e32 v40, v2
	v_mov_b32_e32 v41, v2
	v_mov_b32_e32 v46, v2
	v_mov_b32_e32 v47, v2
	v_mov_b32_e32 v48, v2
	v_mov_b32_e32 v49, v2
	v_mov_b32_e32 v54, v2
	v_mov_b32_e32 v55, v2
	v_mov_b32_e32 v56, v2
	v_mov_b32_e32 v57, v2
	v_mov_b32_e32 v10, v2
	v_mov_b32_e32 v11, v2
	v_mov_b32_e32 v12, v2
	v_mov_b32_e32 v13, v2
	v_mov_b32_e32 v18, v2
	v_mov_b32_e32 v19, v2
	v_mov_b32_e32 v20, v2
	v_mov_b32_e32 v21, v2
	v_mov_b32_e32 v26, v2
	v_mov_b32_e32 v27, v2
	v_mov_b32_e32 v28, v2
	v_mov_b32_e32 v29, v2
	v_mov_b32_e32 v34, v2
	v_mov_b32_e32 v35, v2
	v_mov_b32_e32 v36, v2
	v_mov_b32_e32 v37, v2
	v_mov_b32_e32 v42, v2
	v_mov_b32_e32 v43, v2
	v_mov_b32_e32 v44, v2
	v_mov_b32_e32 v45, v2
	v_mov_b32_e32 v50, v2
	v_mov_b32_e32 v51, v2
	v_mov_b32_e32 v52, v2
	v_mov_b32_e32 v53, v2
	v_mov_b32_e32 v58, v2
	v_mov_b32_e32 v59, v2
	v_mov_b32_e32 v60, v2
	v_mov_b32_e32 v61, v2
	v_mov_b32_e32 v62, v2
	v_mov_b32_e32 v63, v2
	v_mov_b32_e32 v64, v2
	v_mov_b32_e32 v65, v2
	v_mov_b32_e32 v66, v2
	v_mov_b32_e32 v67, v2
	v_mov_b32_e32 v68, v2
	v_mov_b32_e32 v69, v2
	v_mov_b32_e32 v70, v2
	v_mov_b32_e32 v71, v2
	v_mov_b32_e32 v72, v2
	v_mov_b32_e32 v73, v2
	v_mov_b32_e32 v78, v2
	v_mov_b32_e32 v79, v2
	v_mov_b32_e32 v80, v2
	v_mov_b32_e32 v81, v2
	v_mov_b32_e32 v86, v2
	v_mov_b32_e32 v87, v2
	v_mov_b32_e32 v88, v2
	v_mov_b32_e32 v89, v2
	v_mov_b32_e32 v94, v2
	v_mov_b32_e32 v95, v2
	v_mov_b32_e32 v96, v2
	v_mov_b32_e32 v97, v2
	v_mov_b32_e32 v102, v2
	v_mov_b32_e32 v103, v2
	v_mov_b32_e32 v104, v2
	v_mov_b32_e32 v105, v2
	v_mov_b32_e32 v110, v2
	v_mov_b32_e32 v111, v2
	v_mov_b32_e32 v112, v2
	v_mov_b32_e32 v113, v2
	v_mov_b32_e32 v118, v2
	v_mov_b32_e32 v119, v2
	v_mov_b32_e32 v120, v2
	v_mov_b32_e32 v121, v2
	v_mov_b32_e32 v74, v2
	v_mov_b32_e32 v75, v2
	v_mov_b32_e32 v76, v2
	v_mov_b32_e32 v77, v2
	v_mov_b32_e32 v82, v2
	v_mov_b32_e32 v83, v2
	v_mov_b32_e32 v84, v2
	v_mov_b32_e32 v85, v2
	v_mov_b32_e32 v90, v2
	v_mov_b32_e32 v91, v2
	v_mov_b32_e32 v92, v2
	v_mov_b32_e32 v93, v2
	v_mov_b32_e32 v98, v2
	v_mov_b32_e32 v99, v2
	v_mov_b32_e32 v100, v2
	v_mov_b32_e32 v101, v2
	v_mov_b32_e32 v106, v2
	v_mov_b32_e32 v107, v2
	v_mov_b32_e32 v108, v2
	v_mov_b32_e32 v109, v2
	v_mov_b32_e32 v114, v2
	v_mov_b32_e32 v115, v2
	v_mov_b32_e32 v116, v2
	v_mov_b32_e32 v117, v2
	v_mov_b32_e32 v122, v2
	v_mov_b32_e32 v123, v2
	v_mov_b32_e32 v124, v2
	v_mov_b32_e32 v125, v2
	v_mov_b32_e32 v126, v2
	v_mov_b32_e32 v127, v2
	v_mov_b32_e32 v128, v2
	v_mov_b32_e32 v129, v2
	s_add_u32 s26, s24, 0xfffc0080
	s_addc_u32 s27, s25, -1
	s_add_i32 s63, 0, 0x10000
	s_cmp_eq_u32 s62, 12
	s_cselect_b32 s29, s13, s27
	s_cselect_b32 s28, s15, s26
	s_cselect_b32 s27, s11, s61
	s_cselect_b32 s26, s59, s60
	s_add_i32 s67, 0, 0x14000
.LBB0_1027:
	v_add_u32_e32 v156, s63, v145
	v_add_u32_e32 v172, s67, v145
	ds_read_b128 v[140:143], v156
	ds_read_b128 v[148:151], v156 offset:1024
	ds_read_b128 v[152:155], v156 offset:2048
	ds_read_b128 v[156:159], v156 offset:3072
	ds_read_b128 v[160:163], v172
	ds_read_b128 v[164:167], v172 offset:1024
	ds_read_b128 v[168:171], v172 offset:2048
	ds_read_b128 v[172:175], v172 offset:3072
	v_lshl_add_u64 v[180:181], s[24:25], 0, v[136:137]
	s_add_i32 m0, s19, 0xc000
	ds_read_b128 v[176:179], v147
	ds_read_b128 v[186:189], v147 offset:1024
	ds_read_b128 v[190:193], v147 offset:2048
	ds_read_b128 v[212:215], v147 offset:3072
	ds_read_b128 v[216:219], v147 offset:4096
	ds_read_b128 v[220:223], v147 offset:5120
	ds_read_b128 v[224:227], v147 offset:6144
	ds_read_b128 v[228:231], v147 offset:7168
	global_load_lds_dwordx4 v[180:181], off
	v_lshl_add_u64 v[180:181], s[24:25], 0, v[138:139]
	s_add_i32 m0, s19, 0xe000
	s_nop 0
	global_load_lds_dwordx4 v[180:181], off
	s_waitcnt vmcnt(8)
	s_waitcnt lgkmcnt(0)
	s_barrier
	s_setprio 1
	s_waitcnt lgkmcnt(0)
	v_mfma_f32_16x16x32_bf16 v[126:129], v[140:143], v[176:179], v[126:129]
	v_mfma_f32_16x16x32_bf16 v[122:125], v[152:155], v[176:179], v[122:125]
	v_mfma_f32_16x16x32_bf16 v[114:117], v[140:143], v[190:193], v[114:117]
	v_mfma_f32_16x16x32_bf16 v[106:109], v[152:155], v[190:193], v[106:109]
	v_mfma_f32_16x16x32_bf16 v[98:101], v[140:143], v[216:219], v[98:101]
	v_mfma_f32_16x16x32_bf16 v[90:93], v[152:155], v[216:219], v[90:93]
	v_mfma_f32_16x16x32_bf16 v[82:85], v[140:143], v[224:227], v[82:85]
	v_mfma_f32_16x16x32_bf16 v[74:77], v[152:155], v[224:227], v[74:77]
	v_mfma_f32_16x16x32_bf16 v[126:129], v[148:151], v[186:189], v[126:129]
	v_mfma_f32_16x16x32_bf16 v[122:125], v[156:159], v[186:189], v[122:125]
	v_mfma_f32_16x16x32_bf16 v[114:117], v[148:151], v[212:215], v[114:117]
	v_mfma_f32_16x16x32_bf16 v[106:109], v[156:159], v[212:215], v[106:109]
	v_mfma_f32_16x16x32_bf16 v[98:101], v[148:151], v[220:223], v[98:101]
	v_mfma_f32_16x16x32_bf16 v[90:93], v[156:159], v[220:223], v[90:93]
	v_mfma_f32_16x16x32_bf16 v[82:85], v[148:151], v[228:231], v[82:85]
	v_mfma_f32_16x16x32_bf16 v[74:77], v[156:159], v[228:231], v[74:77]
	s_setprio 0
	s_setprio 1
	v_mfma_f32_16x16x32_bf16 v[118:121], v[160:163], v[176:179], v[118:121]
	v_mfma_f32_16x16x32_bf16 v[110:113], v[168:171], v[176:179], v[110:113]
	v_mfma_f32_16x16x32_bf16 v[102:105], v[160:163], v[190:193], v[102:105]
	v_mfma_f32_16x16x32_bf16 v[94:97], v[168:171], v[190:193], v[94:97]
	v_mfma_f32_16x16x32_bf16 v[86:89], v[160:163], v[216:219], v[86:89]
	v_mfma_f32_16x16x32_bf16 v[78:81], v[168:171], v[216:219], v[78:81]
	v_mfma_f32_16x16x32_bf16 v[70:73], v[160:163], v[224:227], v[70:73]
	v_mfma_f32_16x16x32_bf16 v[66:69], v[168:171], v[224:227], v[66:69]
	v_mfma_f32_16x16x32_bf16 v[118:121], v[164:167], v[186:189], v[118:121]
	v_mfma_f32_16x16x32_bf16 v[110:113], v[172:175], v[186:189], v[110:113]
	v_mfma_f32_16x16x32_bf16 v[102:105], v[164:167], v[212:215], v[102:105]
	v_mfma_f32_16x16x32_bf16 v[94:97], v[172:175], v[212:215], v[94:97]
	v_mfma_f32_16x16x32_bf16 v[86:89], v[164:167], v[220:223], v[86:89]
	v_mfma_f32_16x16x32_bf16 v[78:81], v[172:175], v[220:223], v[78:81]
	v_mfma_f32_16x16x32_bf16 v[70:73], v[164:167], v[228:231], v[70:73]
	v_mfma_f32_16x16x32_bf16 v[66:69], v[172:175], v[228:231], v[66:69]
	s_setprio 0
	s_barrier
	s_add_i32 s63, s63, s51
	v_lshl_add_u64 v[180:181], s[26:27], 0, v[0:1]
	s_mov_b32 m0, s63
	ds_read_b128 v[176:179], v147 offset:16384
	ds_read_b128 v[186:189], v147 offset:17408
	ds_read_b128 v[190:193], v147 offset:18432
	ds_read_b128 v[212:215], v147 offset:19456
	ds_read_b128 v[216:219], v147 offset:20480
	ds_read_b128 v[220:223], v147 offset:21504
	ds_read_b128 v[224:227], v147 offset:22528
	ds_read_b128 v[228:231], v147 offset:23552
	global_load_lds_dwordx4 v[180:181], off
	s_add_i32 m0, s63, 0x2000
	s_add_u32 s64, s26, 0x40000
	v_lshl_add_u64 v[194:195], s[26:27], 0, v[134:135]
	s_addc_u32 s65, s27, 0
	s_add_i32 s63, s67, s51
	global_load_lds_dwordx4 v[194:195], off
	v_lshl_add_u64 v[232:233], s[64:65], 0, v[0:1]
	s_mov_b32 m0, s63
	v_lshl_add_u64 v[234:235], s[28:29], 0, v[132:133]
	global_load_lds_dwordx4 v[232:233], off
	v_lshl_add_u64 v[232:233], s[64:65], 0, v[134:135]
	s_add_i32 m0, s63, 0x2000
	s_nop 0
	global_load_lds_dwordx4 v[232:233], off
	v_lshl_add_u64 v[232:233], s[28:29], 0, v[130:131]
	s_mov_b32 m0, s19
	s_nop 0
	global_load_lds_dwordx4 v[232:233], off
	s_mov_b32 m0, s52
	s_nop 0
	global_load_lds_dwordx4 v[234:235], off
	s_waitcnt vmcnt(8)
	s_waitcnt lgkmcnt(0)
	s_barrier
	s_setprio 1
	s_waitcnt lgkmcnt(0)
	v_mfma_f32_16x16x32_bf16 v[62:65], v[140:143], v[176:179], v[62:65]
	v_mfma_f32_16x16x32_bf16 v[58:61], v[152:155], v[176:179], v[58:61]
	v_mfma_f32_16x16x32_bf16 v[50:53], v[140:143], v[190:193], v[50:53]
	v_mfma_f32_16x16x32_bf16 v[42:45], v[152:155], v[190:193], v[42:45]
	v_mfma_f32_16x16x32_bf16 v[34:37], v[140:143], v[216:219], v[34:37]
	v_mfma_f32_16x16x32_bf16 v[26:29], v[152:155], v[216:219], v[26:29]
	v_mfma_f32_16x16x32_bf16 v[18:21], v[140:143], v[224:227], v[18:21]
	v_mfma_f32_16x16x32_bf16 v[10:13], v[152:155], v[224:227], v[10:13]
	v_mfma_f32_16x16x32_bf16 v[62:65], v[148:151], v[186:189], v[62:65]
	v_mfma_f32_16x16x32_bf16 v[58:61], v[156:159], v[186:189], v[58:61]
	v_mfma_f32_16x16x32_bf16 v[50:53], v[148:151], v[212:215], v[50:53]
	v_mfma_f32_16x16x32_bf16 v[42:45], v[156:159], v[212:215], v[42:45]
	v_mfma_f32_16x16x32_bf16 v[34:37], v[148:151], v[220:223], v[34:37]
	v_mfma_f32_16x16x32_bf16 v[26:29], v[156:159], v[220:223], v[26:29]
	v_mfma_f32_16x16x32_bf16 v[18:21], v[148:151], v[228:231], v[18:21]
	v_mfma_f32_16x16x32_bf16 v[10:13], v[156:159], v[228:231], v[10:13]
	s_setprio 0
	s_setprio 1
	v_mfma_f32_16x16x32_bf16 v[54:57], v[160:163], v[176:179], v[54:57]
	v_mfma_f32_16x16x32_bf16 v[46:49], v[168:171], v[176:179], v[46:49]
	v_mfma_f32_16x16x32_bf16 v[38:41], v[160:163], v[190:193], v[38:41]
	v_mfma_f32_16x16x32_bf16 v[30:33], v[168:171], v[190:193], v[30:33]
	v_mfma_f32_16x16x32_bf16 v[22:25], v[160:163], v[216:219], v[22:25]
	v_mfma_f32_16x16x32_bf16 v[14:17], v[168:171], v[216:219], v[14:17]
	v_mfma_f32_16x16x32_bf16 v[6:9], v[160:163], v[224:227], v[6:9]
	v_mfma_f32_16x16x32_bf16 v[2:5], v[168:171], v[224:227], v[2:5]
	v_mfma_f32_16x16x32_bf16 v[54:57], v[164:167], v[186:189], v[54:57]
	v_mfma_f32_16x16x32_bf16 v[46:49], v[172:175], v[186:189], v[46:49]
	v_mfma_f32_16x16x32_bf16 v[38:41], v[164:167], v[212:215], v[38:41]
	v_mfma_f32_16x16x32_bf16 v[30:33], v[172:175], v[212:215], v[30:33]
	v_mfma_f32_16x16x32_bf16 v[22:25], v[164:167], v[220:223], v[22:25]
	v_mfma_f32_16x16x32_bf16 v[14:17], v[172:175], v[220:223], v[14:17]
	v_mfma_f32_16x16x32_bf16 v[6:9], v[164:167], v[228:231], v[6:9]
	v_mfma_f32_16x16x32_bf16 v[2:5], v[172:175], v[228:231], v[2:5]
	s_setprio 0
	s_barrier
	s_add_i32 s63, 0, 0x18000
	s_add_i32 s64, 0, 0x1c000
	v_add_u32_e32 v156, s63, v145
	v_add_u32_e32 v172, s64, v145
	ds_read_b128 v[140:143], v156
	ds_read_b128 v[148:151], v156 offset:1024
	ds_read_b128 v[152:155], v156 offset:2048
	ds_read_b128 v[156:159], v156 offset:3072
	ds_read_b128 v[160:163], v172
	ds_read_b128 v[164:167], v172 offset:1024
	ds_read_b128 v[168:171], v172 offset:2048
	ds_read_b128 v[172:175], v172 offset:3072
	s_add_u32 s28, s28, 0x40000
	s_addc_u32 s29, s29, 0
	s_mov_b32 m0, s53
	v_lshl_add_u64 v[236:237], s[28:29], 0, v[130:131]
	ds_read_b128 v[176:179], v147 offset:32768
	ds_read_b128 v[186:189], v147 offset:33792
	ds_read_b128 v[190:193], v147 offset:34816
	ds_read_b128 v[212:215], v147 offset:35840
	ds_read_b128 v[216:219], v147 offset:36864
	ds_read_b128 v[220:223], v147 offset:37888
	ds_read_b128 v[224:227], v147 offset:38912
	ds_read_b128 v[228:231], v147 offset:39936
	global_load_lds_dwordx4 v[236:237], off
	v_lshl_add_u64 v[236:237], s[28:29], 0, v[132:133]
	s_mov_b32 m0, s54
	s_nop 0
	global_load_lds_dwordx4 v[236:237], off
	s_waitcnt vmcnt(8)
	s_waitcnt lgkmcnt(0)
	s_barrier
	s_setprio 1
	s_waitcnt lgkmcnt(0)
	v_mfma_f32_16x16x32_bf16 v[126:129], v[140:143], v[176:179], v[126:129]
	v_mfma_f32_16x16x32_bf16 v[122:125], v[152:155], v[176:179], v[122:125]
	v_mfma_f32_16x16x32_bf16 v[114:117], v[140:143], v[190:193], v[114:117]
	v_mfma_f32_16x16x32_bf16 v[106:109], v[152:155], v[190:193], v[106:109]
	v_mfma_f32_16x16x32_bf16 v[98:101], v[140:143], v[216:219], v[98:101]
	v_mfma_f32_16x16x32_bf16 v[90:93], v[152:155], v[216:219], v[90:93]
	v_mfma_f32_16x16x32_bf16 v[82:85], v[140:143], v[224:227], v[82:85]
	v_mfma_f32_16x16x32_bf16 v[74:77], v[152:155], v[224:227], v[74:77]
	v_mfma_f32_16x16x32_bf16 v[126:129], v[148:151], v[186:189], v[126:129]
	v_mfma_f32_16x16x32_bf16 v[122:125], v[156:159], v[186:189], v[122:125]
	v_mfma_f32_16x16x32_bf16 v[114:117], v[148:151], v[212:215], v[114:117]
	v_mfma_f32_16x16x32_bf16 v[106:109], v[156:159], v[212:215], v[106:109]
	v_mfma_f32_16x16x32_bf16 v[98:101], v[148:151], v[220:223], v[98:101]
	v_mfma_f32_16x16x32_bf16 v[90:93], v[156:159], v[220:223], v[90:93]
	v_mfma_f32_16x16x32_bf16 v[82:85], v[148:151], v[228:231], v[82:85]
	v_mfma_f32_16x16x32_bf16 v[74:77], v[156:159], v[228:231], v[74:77]
	s_setprio 0
	s_setprio 1
	v_mfma_f32_16x16x32_bf16 v[118:121], v[160:163], v[176:179], v[118:121]
	v_mfma_f32_16x16x32_bf16 v[110:113], v[168:171], v[176:179], v[110:113]
	v_mfma_f32_16x16x32_bf16 v[102:105], v[160:163], v[190:193], v[102:105]
	v_mfma_f32_16x16x32_bf16 v[94:97], v[168:171], v[190:193], v[94:97]
	v_mfma_f32_16x16x32_bf16 v[86:89], v[160:163], v[216:219], v[86:89]
	v_mfma_f32_16x16x32_bf16 v[78:81], v[168:171], v[216:219], v[78:81]
	v_mfma_f32_16x16x32_bf16 v[70:73], v[160:163], v[224:227], v[70:73]
	v_mfma_f32_16x16x32_bf16 v[66:69], v[168:171], v[224:227], v[66:69]
	v_mfma_f32_16x16x32_bf16 v[118:121], v[164:167], v[186:189], v[118:121]
	v_mfma_f32_16x16x32_bf16 v[110:113], v[172:175], v[186:189], v[110:113]
	v_mfma_f32_16x16x32_bf16 v[102:105], v[164:167], v[212:215], v[102:105]
	v_mfma_f32_16x16x32_bf16 v[94:97], v[172:175], v[212:215], v[94:97]
	v_mfma_f32_16x16x32_bf16 v[86:89], v[164:167], v[220:223], v[86:89]
	v_mfma_f32_16x16x32_bf16 v[78:81], v[172:175], v[220:223], v[78:81]
	v_mfma_f32_16x16x32_bf16 v[70:73], v[164:167], v[228:231], v[70:73]
	v_mfma_f32_16x16x32_bf16 v[66:69], v[172:175], v[228:231], v[66:69]
	s_setprio 0
	s_barrier
	s_add_i32 s28, s63, s51
	v_lshl_add_u64 v[180:181], v[180:181], 0, s[16:17]
	s_mov_b32 m0, s28
	ds_read_b128 v[176:179], v147 offset:49152
	ds_read_b128 v[186:189], v147 offset:50176
	ds_read_b128 v[190:193], v147 offset:51200
	ds_read_b128 v[212:215], v147 offset:52224
	ds_read_b128 v[216:219], v147 offset:53248
	ds_read_b128 v[220:223], v147 offset:54272
	ds_read_b128 v[224:227], v147 offset:55296
	ds_read_b128 v[228:231], v147 offset:56320
	global_load_lds_dwordx4 v[180:181], off
	s_add_i32 m0, s28, 0x2000
	s_add_u32 s26, s26, 0x40080
	v_lshl_add_u64 v[180:181], v[194:195], 0, s[16:17]
	s_addc_u32 s27, s27, 0
	s_add_i32 s28, s64, s51
	global_load_lds_dwordx4 v[180:181], off
	v_lshl_add_u64 v[180:181], s[26:27], 0, v[0:1]
	s_mov_b32 m0, s28
	s_nop 0
	global_load_lds_dwordx4 v[180:181], off
	v_lshl_add_u64 v[180:181], s[26:27], 0, v[134:135]
	s_add_i32 m0, s28, 0x2000
	s_nop 0
	global_load_lds_dwordx4 v[180:181], off
	v_lshl_add_u64 v[180:181], v[232:233], 0, s[16:17]
	s_mov_b32 m0, s56
	s_nop 0
	global_load_lds_dwordx4 v[180:181], off
	v_lshl_add_u64 v[180:181], v[234:235], 0, s[16:17]
	s_mov_b32 m0, s57
	s_nop 0
	global_load_lds_dwordx4 v[180:181], off
	s_waitcnt vmcnt(8)
	s_waitcnt lgkmcnt(0)
	s_barrier
	s_setprio 1
	s_waitcnt lgkmcnt(0)
	v_mfma_f32_16x16x32_bf16 v[62:65], v[140:143], v[176:179], v[62:65]
	v_mfma_f32_16x16x32_bf16 v[58:61], v[152:155], v[176:179], v[58:61]
	v_mfma_f32_16x16x32_bf16 v[50:53], v[140:143], v[190:193], v[50:53]
	v_mfma_f32_16x16x32_bf16 v[42:45], v[152:155], v[190:193], v[42:45]
	v_mfma_f32_16x16x32_bf16 v[34:37], v[140:143], v[216:219], v[34:37]
	v_mfma_f32_16x16x32_bf16 v[26:29], v[152:155], v[216:219], v[26:29]
	v_mfma_f32_16x16x32_bf16 v[18:21], v[140:143], v[224:227], v[18:21]
	v_mfma_f32_16x16x32_bf16 v[10:13], v[152:155], v[224:227], v[10:13]
	v_mfma_f32_16x16x32_bf16 v[62:65], v[148:151], v[186:189], v[62:65]
	v_mfma_f32_16x16x32_bf16 v[58:61], v[156:159], v[186:189], v[58:61]
	v_mfma_f32_16x16x32_bf16 v[50:53], v[148:151], v[212:215], v[50:53]
	v_mfma_f32_16x16x32_bf16 v[42:45], v[156:159], v[212:215], v[42:45]
	v_mfma_f32_16x16x32_bf16 v[34:37], v[148:151], v[220:223], v[34:37]
	v_mfma_f32_16x16x32_bf16 v[26:29], v[156:159], v[220:223], v[26:29]
	v_mfma_f32_16x16x32_bf16 v[18:21], v[148:151], v[228:231], v[18:21]
	v_mfma_f32_16x16x32_bf16 v[10:13], v[156:159], v[228:231], v[10:13]
	s_setprio 0
	s_setprio 1
	v_mfma_f32_16x16x32_bf16 v[54:57], v[160:163], v[176:179], v[54:57]
	v_mfma_f32_16x16x32_bf16 v[46:49], v[168:171], v[176:179], v[46:49]
	v_mfma_f32_16x16x32_bf16 v[38:41], v[160:163], v[190:193], v[38:41]
	v_mfma_f32_16x16x32_bf16 v[30:33], v[168:171], v[190:193], v[30:33]
	v_mfma_f32_16x16x32_bf16 v[22:25], v[160:163], v[216:219], v[22:25]
	v_mfma_f32_16x16x32_bf16 v[14:17], v[168:171], v[216:219], v[14:17]
	v_mfma_f32_16x16x32_bf16 v[6:9], v[160:163], v[224:227], v[6:9]
	v_mfma_f32_16x16x32_bf16 v[2:5], v[168:171], v[224:227], v[2:5]
	v_mfma_f32_16x16x32_bf16 v[54:57], v[164:167], v[186:189], v[54:57]
	v_mfma_f32_16x16x32_bf16 v[46:49], v[172:175], v[186:189], v[46:49]
	v_mfma_f32_16x16x32_bf16 v[38:41], v[164:167], v[212:215], v[38:41]
	v_mfma_f32_16x16x32_bf16 v[30:33], v[172:175], v[212:215], v[30:33]
	v_mfma_f32_16x16x32_bf16 v[22:25], v[164:167], v[220:223], v[22:25]
	v_mfma_f32_16x16x32_bf16 v[14:17], v[172:175], v[220:223], v[14:17]
	v_mfma_f32_16x16x32_bf16 v[6:9], v[164:167], v[228:231], v[6:9]
	v_mfma_f32_16x16x32_bf16 v[2:5], v[172:175], v[228:231], v[2:5]
	s_setprio 0
	s_add_i32 s62, s62, 2
	s_add_u32 s24, s24, 0x100
	s_addc_u32 s25, s25, 0
	s_add_u32 s60, s60, 0x100
	s_addc_u32 s61, s61, 0
	s_add_u32 s26, s24, 0xfffc0080
	s_addc_u32 s27, s25, -1
	s_add_i32 s63, 0, 0x10000
	s_cmp_eq_u32 s62, 12
	s_cselect_b32 s29, s13, s27
	s_cselect_b32 s28, s15, s26
	s_cselect_b32 s27, s11, s61
	s_cselect_b32 s26, s59, s60
	s_add_i32 s67, 0, 0x14000
	s_cmp_gt_u32 s62, 13
	s_barrier
	s_cbranch_scc0 .LBB0_1027
	s_and_b64 vcc, exec, s[8:9]
	s_cbranch_vccz .LBB0_1030
	s_barrier
